# GEMM K-loops: loop-carried scalar updates and exit compare moved ahead of the loop-back barrier (back-edge rotation, 4 loops)
# baseline (speedup 1.0000x reference)
; #define PG8_STAGE(bufoff, gbase, voff) do { _Pragma("unroll") for (int _i = 0; _i < 2; ++_i) \
;         __builtin_amdgcn_global_load_lds((const unsigned*)((const char*)(gbase) + (voff)[_i]), (LAS unsigned*)(lds + (bufoff) + ldsw + _i * 8192), 16, 0, 0); } while (0)
; #define PG8_LDA(dst, b, h) do { _Pragma("unroll") for (int m = 0; m < 4; ++m) _Pragma("unroll") for (int k = 0; k < 2; ++k) dst[m][k] = *(const LAS bf16x8*)(lds + PG8_SA(b, h) + aoff + m * 2048 + k * 1024); } while (0)
; #define PG8_LDB(dst, b, h) do { _Pragma("unroll") for (int n = 0; n < 2; ++n) _Pragma("unroll") for (int k = 0; k < 2; ++k) dst[n][k] = *(const LAS bf16x8*)(lds + PG8_SB(b, h) + boff + n * 2048 + k * 1024); } while (0)
; #define PG8_MMA(ai, bj, At, Bt) do { __builtin_amdgcn_s_setprio(1); _Pragma("unroll") for (int m = 0; m < 4; ++m) _Pragma("unroll") for (int n = 0; n < 2; ++n) _Pragma("unroll") for (int k = 0; k < 2; ++k) \
;         acc[ai][bj][m][n] = __builtin_amdgcn_mfma_f32_16x16x32_bf16(Bt[n][k], At[m][k], acc[ai][bj][m][n], 0, 0, 0); __builtin_amdgcn_s_setprio(0); } while (0)
; #define PG8_WAIT_V(n) asm volatile("s_waitcnt vmcnt(" #n ")" ::: "memory")
; #define PG8_WAIT_L(n) asm volatile("s_waitcnt lgkmcnt(" #n ")" ::: "memory")
; #define PG8_BAR __builtin_amdgcn_s_barrier()
; #define PG8_SCHED __builtin_amdgcn_sched_barrier(0)
; template <class Epi, class Sched, bool ALIGN_EPI = false, bool SP2 = false>
; __device__ __forceinline__ void gemm_phase(LAS unsigned char* lds, const Gemm g, const Sched& S, const Epi& E, const int tid) {
;     ...
;             PG8_LDB(B0, 0, 0); PG8_LDB(B1, 0, 1); PG8_SCHED; PG8_LDA(At, 0, 0); PG8_STAGE(PG8_SA(1, 1), a1 + hstep, voffA);
;             PG8_WAIT_V(8); PG8_WAIT_L(0); PG8_BAR; PG8_MMA(0, 0, At, B0); PG8_MMA(0, 1, At, B1); PG8_BAR; PG8_SCHED;
;             PG8_LDA(At, 0, 1); PG8_STAGE(PG8_SB(0, 0), b2, voffB); PG8_STAGE(PG8_SB(0, 1), b2 + hstep, voffB); PG8_STAGE(PG8_SA(0, 0), a2, voffA);
.LBB0_613:
	s_add_u32 s8, s6, 0xfffc0080
	s_addc_u32 s9, s7, -1
	s_add_i32 s40, 0, 0x10000
	s_cmp_eq_u32 s39, 12
	s_cselect_b32 s11, s12, s9
	s_cselect_b32 s10, s13, s8
	v_add_u32_e32 v0, s40, v196
	s_cselect_b32 s9, s27, s38
	s_cselect_b32 s8, s29, s37
	s_add_i32 s42, 0, 0x14000
	ds_read_b128 v[34:37], v0
	ds_read_b128 v[38:41], v0 offset:1024
	ds_read_b128 v[42:45], v0 offset:2048
	ds_read_b128 v[46:49], v0 offset:3072
	v_add_u32_e32 v0, s42, v196
	ds_read_b128 v[146:149], v0
	ds_read_b128 v[150:153], v0 offset:1024
	ds_read_b128 v[154:157], v0 offset:2048
	ds_read_b128 v[184:187], v0 offset:3072
	v_lshl_add_u64 v[236:237], s[6:7], 0, v[180:181]
	s_add_i32 m0, s49, 0xc000
	ds_read_b128 v[188:191], v209
	ds_read_b128 v[192:195], v209 offset:1024
	ds_read_b128 v[212:215], v209 offset:2048
	ds_read_b128 v[216:219], v209 offset:3072
	ds_read_b128 v[220:223], v209 offset:4096
	ds_read_b128 v[224:227], v209 offset:5120
	ds_read_b128 v[228:231], v209 offset:6144
	ds_read_b128 v[232:235], v209 offset:7168
	global_load_lds_dwordx4 v[236:237], off
	v_lshl_add_u64 v[236:237], s[6:7], 0, v[182:183]
	s_add_i32 m0, s49, 0xe000
	s_nop 0
	global_load_lds_dwordx4 v[236:237], off
	s_waitcnt vmcnt(8)
	s_waitcnt lgkmcnt(0)
	s_barrier
	s_setprio 1
	s_waitcnt lgkmcnt(0)
	v_mfma_f32_16x16x32_bf16 v[142:145], v[34:37], v[188:191], v[142:145]
	v_mfma_f32_16x16x32_bf16 v[138:141], v[42:45], v[188:191], v[138:141]
	v_mfma_f32_16x16x32_bf16 v[126:129], v[34:37], v[212:215], v[126:129]
	v_mfma_f32_16x16x32_bf16 v[122:125], v[42:45], v[212:215], v[122:125]
	v_mfma_f32_16x16x32_bf16 v[110:113], v[34:37], v[220:223], v[110:113]
	v_mfma_f32_16x16x32_bf16 v[106:109], v[42:45], v[220:223], v[106:109]
	v_mfma_f32_16x16x32_bf16 v[94:97], v[34:37], v[228:231], v[94:97]
	v_mfma_f32_16x16x32_bf16 v[90:93], v[42:45], v[228:231], v[90:93]
	v_mfma_f32_16x16x32_bf16 v[142:145], v[38:41], v[192:195], v[142:145]
	v_mfma_f32_16x16x32_bf16 v[138:141], v[46:49], v[192:195], v[138:141]
	v_mfma_f32_16x16x32_bf16 v[126:129], v[38:41], v[216:219], v[126:129]
	v_mfma_f32_16x16x32_bf16 v[122:125], v[46:49], v[216:219], v[122:125]
	v_mfma_f32_16x16x32_bf16 v[110:113], v[38:41], v[224:227], v[110:113]
	v_mfma_f32_16x16x32_bf16 v[106:109], v[46:49], v[224:227], v[106:109]
	v_mfma_f32_16x16x32_bf16 v[94:97], v[38:41], v[232:235], v[94:97]
	v_mfma_f32_16x16x32_bf16 v[90:93], v[46:49], v[232:235], v[90:93]
	s_setprio 0
	s_setprio 1
	v_mfma_f32_16x16x32_bf16 v[134:137], v[146:149], v[188:191], v[134:137]
	v_mfma_f32_16x16x32_bf16 v[130:133], v[154:157], v[188:191], v[130:133]
	v_mfma_f32_16x16x32_bf16 v[118:121], v[146:149], v[212:215], v[118:121]
	v_mfma_f32_16x16x32_bf16 v[114:117], v[154:157], v[212:215], v[114:117]
	v_mfma_f32_16x16x32_bf16 v[102:105], v[146:149], v[220:223], v[102:105]
	v_mfma_f32_16x16x32_bf16 v[98:101], v[154:157], v[220:223], v[98:101]
	v_mfma_f32_16x16x32_bf16 v[86:89], v[146:149], v[228:231], v[86:89]
	v_mfma_f32_16x16x32_bf16 v[82:85], v[154:157], v[228:231], v[82:85]
	v_mfma_f32_16x16x32_bf16 v[134:137], v[150:153], v[192:195], v[134:137]
	v_mfma_f32_16x16x32_bf16 v[130:133], v[184:187], v[192:195], v[130:133]
	v_mfma_f32_16x16x32_bf16 v[118:121], v[150:153], v[216:219], v[118:121]
	v_mfma_f32_16x16x32_bf16 v[114:117], v[184:187], v[216:219], v[114:117]
	v_mfma_f32_16x16x32_bf16 v[102:105], v[150:153], v[224:227], v[102:105]
	v_mfma_f32_16x16x32_bf16 v[98:101], v[184:187], v[224:227], v[98:101]
	v_mfma_f32_16x16x32_bf16 v[86:89], v[150:153], v[232:235], v[86:89]
	v_mfma_f32_16x16x32_bf16 v[82:85], v[184:187], v[232:235], v[82:85]
	s_setprio 0
	s_barrier
	s_add_i32 s40, s40, s48
	v_lshl_add_u64 v[236:237], s[8:9], 0, v[174:175]
	s_mov_b32 m0, s40
	ds_read_b128 v[188:191], v209 offset:16384
	ds_read_b128 v[192:195], v209 offset:17408
	ds_read_b128 v[212:215], v209 offset:18432
	ds_read_b128 v[216:219], v209 offset:19456
	ds_read_b128 v[220:223], v209 offset:20480
	ds_read_b128 v[224:227], v209 offset:21504
	ds_read_b128 v[228:231], v209 offset:22528
	ds_read_b128 v[232:235], v209 offset:23552
	global_load_lds_dwordx4 v[236:237], off
	s_add_i32 m0, s40, 0x2000
	s_add_u32 s40, s8, 0x40000
	v_lshl_add_u64 v[238:239], s[8:9], 0, v[158:159]
	s_addc_u32 s41, s9, 0
	s_add_i32 s42, s42, s48
	global_load_lds_dwordx4 v[238:239], off
	v_lshl_add_u64 v[240:241], s[40:41], 0, v[174:175]
	s_mov_b32 m0, s42
	v_lshl_add_u64 v[242:243], s[10:11], 0, v[160:161]
	global_load_lds_dwordx4 v[240:241], off
	v_lshl_add_u64 v[240:241], s[40:41], 0, v[158:159]
	s_add_i32 m0, s42, 0x2000
	s_nop 0
	global_load_lds_dwordx4 v[240:241], off
	v_lshl_add_u64 v[240:241], s[10:11], 0, v[176:177]
	s_mov_b32 m0, s49
	s_nop 0
	global_load_lds_dwordx4 v[240:241], off
	s_mov_b32 m0, s60
	s_nop 0
	global_load_lds_dwordx4 v[242:243], off
	s_waitcnt vmcnt(8)
	s_waitcnt lgkmcnt(0)
	s_barrier
; #define PG8_STAGE(bufoff, gbase, voff) do { _Pragma("unroll") for (int _i = 0; _i < 2; ++_i) \
;         __builtin_amdgcn_global_load_lds((const unsigned*)((const char*)(gbase) + (voff)[_i]), (LAS unsigned*)(lds + (bufoff) + ldsw + _i * 8192), 16, 0, 0); } while (0)
; #define PG8_LDA(dst, b, h) do { _Pragma("unroll") for (int m = 0; m < 4; ++m) _Pragma("unroll") for (int k = 0; k < 2; ++k) dst[m][k] = *(const LAS bf16x8*)(lds + PG8_SA(b, h) + aoff + m * 2048 + k * 1024); } while (0)
; #define PG8_LDB(dst, b, h) do { _Pragma("unroll") for (int n = 0; n < 2; ++n) _Pragma("unroll") for (int k = 0; k < 2; ++k) dst[n][k] = *(const LAS bf16x8*)(lds + PG8_SB(b, h) + boff + n * 2048 + k * 1024); } while (0)
; #define PG8_MMA(ai, bj, At, Bt) do { __builtin_amdgcn_s_setprio(1); _Pragma("unroll") for (int m = 0; m < 4; ++m) _Pragma("unroll") for (int n = 0; n < 2; ++n) _Pragma("unroll") for (int k = 0; k < 2; ++k) \
;         acc[ai][bj][m][n] = __builtin_amdgcn_mfma_f32_16x16x32_bf16(Bt[n][k], At[m][k], acc[ai][bj][m][n], 0, 0, 0); __builtin_amdgcn_s_setprio(0); } while (0)
; #define PG8_WAIT_V(n) asm volatile("s_waitcnt vmcnt(" #n ")" ::: "memory")
; #define PG8_WAIT_L(n) asm volatile("s_waitcnt lgkmcnt(" #n ")" ::: "memory")
; #define PG8_BAR __builtin_amdgcn_s_barrier()
; #define PG8_SCHED __builtin_amdgcn_sched_barrier(0)
; template <class Epi, class Sched, bool ALIGN_EPI = false, bool SP2 = false>
; __device__ __forceinline__ void gemm_phase(LAS unsigned char* lds, const Gemm g, const Sched& S, const Epi& E, const int tid) {
;     ...
;             PG8_WAIT_V(8); PG8_WAIT_L(0); PG8_BAR; PG8_MMA(1, 0, At, B0); PG8_MMA(1, 1, At, B1); PG8_BAR; PG8_SCHED;
;             PG8_LDB(B0, 1, 0); PG8_LDB(B1, 1, 1); PG8_SCHED; PG8_LDA(At, 1, 0); PG8_STAGE(PG8_SA(0, 1), a2 + hstep, voffA);
;             PG8_WAIT_V(8); PG8_WAIT_L(0); PG8_BAR; PG8_MMA(0, 0, At, B0); PG8_MMA(0, 1, At, B1); PG8_BAR; PG8_SCHED;
	s_setprio 1
	s_waitcnt lgkmcnt(0)
	v_mfma_f32_16x16x32_bf16 v[78:81], v[34:37], v[188:191], v[78:81]
	v_mfma_f32_16x16x32_bf16 v[74:77], v[42:45], v[188:191], v[74:77]
	v_mfma_f32_16x16x32_bf16 v[62:65], v[34:37], v[212:215], v[62:65]
	v_mfma_f32_16x16x32_bf16 v[58:61], v[42:45], v[212:215], v[58:61]
	v_mfma_f32_16x16x32_bf16 v[30:33], v[34:37], v[220:223], v[30:33]
	v_mfma_f32_16x16x32_bf16 v[26:29], v[42:45], v[220:223], v[26:29]
	v_mfma_f32_16x16x32_bf16 v[14:17], v[34:37], v[228:231], v[14:17]
	v_mfma_f32_16x16x32_bf16 v[10:13], v[42:45], v[228:231], v[10:13]
	v_mfma_f32_16x16x32_bf16 v[78:81], v[38:41], v[192:195], v[78:81]
	v_mfma_f32_16x16x32_bf16 v[74:77], v[46:49], v[192:195], v[74:77]
	v_mfma_f32_16x16x32_bf16 v[62:65], v[38:41], v[216:219], v[62:65]
	v_mfma_f32_16x16x32_bf16 v[58:61], v[46:49], v[216:219], v[58:61]
	v_mfma_f32_16x16x32_bf16 v[30:33], v[38:41], v[224:227], v[30:33]
	v_mfma_f32_16x16x32_bf16 v[26:29], v[46:49], v[224:227], v[26:29]
	v_mfma_f32_16x16x32_bf16 v[14:17], v[38:41], v[232:235], v[14:17]
	v_mfma_f32_16x16x32_bf16 v[10:13], v[46:49], v[232:235], v[10:13]
	s_setprio 0
	s_setprio 1
	v_mfma_f32_16x16x32_bf16 v[22:25], v[146:149], v[220:223], v[22:25]
	v_mfma_f32_16x16x32_bf16 v[18:21], v[154:157], v[220:223], v[18:21]
	v_mfma_f32_16x16x32_bf16 v[6:9], v[146:149], v[228:231], v[6:9]
	v_mfma_f32_16x16x32_bf16 v[2:5], v[154:157], v[228:231], v[2:5]
	v_mfma_f32_16x16x32_bf16 v[34:37], v[146:149], v[188:191], v[70:73]
	v_mfma_f32_16x16x32_bf16 v[38:41], v[154:157], v[188:191], v[66:69]
	v_mfma_f32_16x16x32_bf16 v[42:45], v[146:149], v[212:215], v[54:57]
	v_mfma_f32_16x16x32_bf16 v[46:49], v[154:157], v[212:215], v[50:53]
	v_mfma_f32_16x16x32_bf16 v[22:25], v[150:153], v[224:227], v[22:25]
	v_mfma_f32_16x16x32_bf16 v[18:21], v[184:187], v[224:227], v[18:21]
	v_mfma_f32_16x16x32_bf16 v[6:9], v[150:153], v[232:235], v[6:9]
	v_mfma_f32_16x16x32_bf16 v[2:5], v[184:187], v[232:235], v[2:5]
	v_mfma_f32_16x16x32_bf16 v[34:37], v[150:153], v[192:195], v[34:37]
	v_mfma_f32_16x16x32_bf16 v[38:41], v[184:187], v[192:195], v[38:41]
	v_mfma_f32_16x16x32_bf16 v[42:45], v[150:153], v[216:219], v[42:45]
	v_mfma_f32_16x16x32_bf16 v[46:49], v[184:187], v[216:219], v[46:49]
	s_setprio 0
	s_barrier
	s_add_i32 s40, 0, 0x18000
	v_add_u32_e32 v0, s40, v196
	ds_read_b128 v[50:53], v0
	ds_read_b128 v[54:57], v0 offset:1024
	ds_read_b128 v[66:69], v0 offset:2048
	ds_read_b128 v[70:73], v0 offset:3072
	v_add_u32_e32 v0, s93, v196
	ds_read_b128 v[146:149], v0
	ds_read_b128 v[150:153], v0 offset:1024
	ds_read_b128 v[154:157], v0 offset:2048
	ds_read_b128 v[184:187], v0 offset:3072
	s_add_u32 s10, s10, 0x40000
	s_addc_u32 s11, s11, 0
	s_mov_b32 m0, s61
	v_lshl_add_u64 v[244:245], s[10:11], 0, v[176:177]
	ds_read_b128 v[188:191], v209 offset:32768
	ds_read_b128 v[192:195], v209 offset:33792
	ds_read_b128 v[212:215], v209 offset:34816
	ds_read_b128 v[216:219], v209 offset:35840
	ds_read_b128 v[220:223], v209 offset:36864
	ds_read_b128 v[224:227], v209 offset:37888
	ds_read_b128 v[228:231], v209 offset:38912
	ds_read_b128 v[232:235], v209 offset:39936
	global_load_lds_dwordx4 v[244:245], off
	v_lshl_add_u64 v[244:245], s[10:11], 0, v[160:161]
	s_mov_b32 m0, s62
	s_nop 0
	global_load_lds_dwordx4 v[244:245], off
	s_waitcnt vmcnt(8)
	s_waitcnt lgkmcnt(0)
	s_barrier
	s_setprio 1
	s_waitcnt lgkmcnt(0)
	v_mfma_f32_16x16x32_bf16 v[142:145], v[50:53], v[188:191], v[142:145]
	v_mfma_f32_16x16x32_bf16 v[138:141], v[66:69], v[188:191], v[138:141]
	v_mfma_f32_16x16x32_bf16 v[126:129], v[50:53], v[212:215], v[126:129]
	v_mfma_f32_16x16x32_bf16 v[122:125], v[66:69], v[212:215], v[122:125]
	v_mfma_f32_16x16x32_bf16 v[110:113], v[50:53], v[220:223], v[110:113]
	v_mfma_f32_16x16x32_bf16 v[106:109], v[66:69], v[220:223], v[106:109]
	v_mfma_f32_16x16x32_bf16 v[94:97], v[50:53], v[228:231], v[94:97]
	v_mfma_f32_16x16x32_bf16 v[90:93], v[66:69], v[228:231], v[90:93]
	v_mfma_f32_16x16x32_bf16 v[142:145], v[54:57], v[192:195], v[142:145]
	v_mfma_f32_16x16x32_bf16 v[138:141], v[70:73], v[192:195], v[138:141]
	v_mfma_f32_16x16x32_bf16 v[126:129], v[54:57], v[216:219], v[126:129]
	v_mfma_f32_16x16x32_bf16 v[122:125], v[70:73], v[216:219], v[122:125]
	v_mfma_f32_16x16x32_bf16 v[110:113], v[54:57], v[224:227], v[110:113]
	v_mfma_f32_16x16x32_bf16 v[106:109], v[70:73], v[224:227], v[106:109]
	v_mfma_f32_16x16x32_bf16 v[94:97], v[54:57], v[232:235], v[94:97]
	v_mfma_f32_16x16x32_bf16 v[90:93], v[70:73], v[232:235], v[90:93]
	s_setprio 0
	s_setprio 1
	v_mfma_f32_16x16x32_bf16 v[134:137], v[146:149], v[188:191], v[134:137]
	v_mfma_f32_16x16x32_bf16 v[130:133], v[154:157], v[188:191], v[130:133]
	v_mfma_f32_16x16x32_bf16 v[118:121], v[146:149], v[212:215], v[118:121]
	v_mfma_f32_16x16x32_bf16 v[114:117], v[154:157], v[212:215], v[114:117]
	v_mfma_f32_16x16x32_bf16 v[102:105], v[146:149], v[220:223], v[102:105]
	v_mfma_f32_16x16x32_bf16 v[98:101], v[154:157], v[220:223], v[98:101]
	v_mfma_f32_16x16x32_bf16 v[86:89], v[146:149], v[228:231], v[86:89]
	v_mfma_f32_16x16x32_bf16 v[82:85], v[154:157], v[228:231], v[82:85]
	v_mfma_f32_16x16x32_bf16 v[134:137], v[150:153], v[192:195], v[134:137]
	v_mfma_f32_16x16x32_bf16 v[130:133], v[184:187], v[192:195], v[130:133]
	v_mfma_f32_16x16x32_bf16 v[118:121], v[150:153], v[216:219], v[118:121]
	v_mfma_f32_16x16x32_bf16 v[114:117], v[184:187], v[216:219], v[114:117]
	v_mfma_f32_16x16x32_bf16 v[102:105], v[150:153], v[224:227], v[102:105]
	v_mfma_f32_16x16x32_bf16 v[98:101], v[184:187], v[224:227], v[98:101]
	v_mfma_f32_16x16x32_bf16 v[86:89], v[150:153], v[232:235], v[86:89]
	v_mfma_f32_16x16x32_bf16 v[82:85], v[184:187], v[232:235], v[82:85]
	s_setprio 0
	s_barrier
; #define PG8_STAGE(bufoff, gbase, voff) do { _Pragma("unroll") for (int _i = 0; _i < 2; ++_i) \
;         __builtin_amdgcn_global_load_lds((const unsigned*)((const char*)(gbase) + (voff)[_i]), (LAS unsigned*)(lds + (bufoff) + ldsw + _i * 8192), 16, 0, 0); } while (0)
; #define PG8_LDA(dst, b, h) do { _Pragma("unroll") for (int m = 0; m < 4; ++m) _Pragma("unroll") for (int k = 0; k < 2; ++k) dst[m][k] = *(const LAS bf16x8*)(lds + PG8_SA(b, h) + aoff + m * 2048 + k * 1024); } while (0)
; #define PG8_MMA(ai, bj, At, Bt) do { __builtin_amdgcn_s_setprio(1); _Pragma("unroll") for (int m = 0; m < 4; ++m) _Pragma("unroll") for (int n = 0; n < 2; ++n) _Pragma("unroll") for (int k = 0; k < 2; ++k) \
;         acc[ai][bj][m][n] = __builtin_amdgcn_mfma_f32_16x16x32_bf16(Bt[n][k], At[m][k], acc[ai][bj][m][n], 0, 0, 0); __builtin_amdgcn_s_setprio(0); } while (0)
; #define PG8_WAIT_V(n) asm volatile("s_waitcnt vmcnt(" #n ")" ::: "memory")
; #define PG8_WAIT_L(n) asm volatile("s_waitcnt lgkmcnt(" #n ")" ::: "memory")
; #define PG8_BAR __builtin_amdgcn_s_barrier()
; #define PG8_SCHED __builtin_amdgcn_sched_barrier(0)
; template <class Epi, class Sched, bool ALIGN_EPI = false, bool SP2 = false>
; __device__ __forceinline__ void gemm_phase(LAS unsigned char* lds, const Gemm g, const Sched& S, const Epi& E, const int tid) {
;     ...
;         for (int t = 0; t < nt; t += 2) {
;             const bool last = (t == nt - 2);
;             const char* a1 = cA + (size_t)(t + 1) * kstep;
;             const char* a2 = last ? nA : cA + (size_t)(t + 2) * kstep; const char* b2 = last ? nB : cB + (size_t)(t + 2) * kstep;
;             const char* a3 = a2 + kstep; const char* b3 = b2 + kstep;
;     ...
;             PG8_LDA(At, 1, 1); PG8_STAGE(PG8_SB(1, 0), b3, voffB); PG8_STAGE(PG8_SB(1, 1), b3 + hstep, voffB); PG8_STAGE(PG8_SA(1, 0), a3, voffA);
;             PG8_WAIT_V(8); PG8_WAIT_L(0); PG8_BAR; PG8_MMA(1, 0, At, B0); PG8_MMA(1, 1, At, B1); PG8_BAR; PG8_SCHED;
	s_add_i32 s10, s40, s48
	v_lshl_add_u64 v[236:237], v[236:237], 0, s[0:1]
	s_mov_b32 m0, s10
	ds_read_b128 v[188:191], v209 offset:49152
	ds_read_b128 v[192:195], v209 offset:50176
	ds_read_b128 v[212:215], v209 offset:51200
	ds_read_b128 v[216:219], v209 offset:52224
	ds_read_b128 v[220:223], v209 offset:53248
	ds_read_b128 v[224:227], v209 offset:54272
	ds_read_b128 v[228:231], v209 offset:55296
	ds_read_b128 v[232:235], v209 offset:56320
	global_load_lds_dwordx4 v[236:237], off
	s_add_i32 m0, s10, 0x2000
	s_add_u32 s8, s8, 0x40080
	v_lshl_add_u64 v[236:237], v[238:239], 0, s[0:1]
	s_addc_u32 s9, s9, 0
	s_add_i32 s10, s93, s48
	global_load_lds_dwordx4 v[236:237], off
	v_lshl_add_u64 v[236:237], s[8:9], 0, v[174:175]
	s_mov_b32 m0, s10
	s_nop 0
	global_load_lds_dwordx4 v[236:237], off
	v_lshl_add_u64 v[236:237], s[8:9], 0, v[158:159]
	s_add_i32 m0, s10, 0x2000
	s_nop 0
	global_load_lds_dwordx4 v[236:237], off
	v_lshl_add_u64 v[236:237], v[240:241], 0, s[0:1]
	s_mov_b32 m0, s68
	s_nop 0
	global_load_lds_dwordx4 v[236:237], off
	v_lshl_add_u64 v[236:237], v[242:243], 0, s[0:1]
	s_mov_b32 m0, s69
	s_nop 0
	global_load_lds_dwordx4 v[236:237], off
	s_waitcnt vmcnt(8)
	s_waitcnt lgkmcnt(0)
	s_barrier
	s_setprio 1
	s_waitcnt lgkmcnt(0)
	v_mfma_f32_16x16x32_bf16 v[78:81], v[50:53], v[188:191], v[78:81]
	v_mfma_f32_16x16x32_bf16 v[74:77], v[66:69], v[188:191], v[74:77]
	v_mfma_f32_16x16x32_bf16 v[62:65], v[50:53], v[212:215], v[62:65]
	v_mfma_f32_16x16x32_bf16 v[58:61], v[66:69], v[212:215], v[58:61]
	v_mfma_f32_16x16x32_bf16 v[30:33], v[50:53], v[220:223], v[30:33]
	v_mfma_f32_16x16x32_bf16 v[26:29], v[66:69], v[220:223], v[26:29]
	v_mfma_f32_16x16x32_bf16 v[14:17], v[50:53], v[228:231], v[14:17]
	v_mfma_f32_16x16x32_bf16 v[10:13], v[66:69], v[228:231], v[10:13]
	v_mfma_f32_16x16x32_bf16 v[78:81], v[54:57], v[192:195], v[78:81]
	v_mfma_f32_16x16x32_bf16 v[74:77], v[70:73], v[192:195], v[74:77]
	v_mfma_f32_16x16x32_bf16 v[62:65], v[54:57], v[216:219], v[62:65]
	v_mfma_f32_16x16x32_bf16 v[58:61], v[70:73], v[216:219], v[58:61]
	v_mfma_f32_16x16x32_bf16 v[30:33], v[54:57], v[224:227], v[30:33]
	v_mfma_f32_16x16x32_bf16 v[26:29], v[70:73], v[224:227], v[26:29]
	v_mfma_f32_16x16x32_bf16 v[14:17], v[54:57], v[232:235], v[14:17]
	v_mfma_f32_16x16x32_bf16 v[10:13], v[70:73], v[232:235], v[10:13]
	s_setprio 0
	s_setprio 1
	v_mfma_f32_16x16x32_bf16 v[34:37], v[146:149], v[188:191], v[34:37]
	v_mfma_f32_16x16x32_bf16 v[70:73], v[150:153], v[192:195], v[34:37]
	v_mfma_f32_16x16x32_bf16 v[34:37], v[154:157], v[188:191], v[38:41]
	v_mfma_f32_16x16x32_bf16 v[66:69], v[184:187], v[192:195], v[34:37]
	v_mfma_f32_16x16x32_bf16 v[34:37], v[146:149], v[212:215], v[42:45]
	v_mfma_f32_16x16x32_bf16 v[54:57], v[150:153], v[216:219], v[34:37]
	v_mfma_f32_16x16x32_bf16 v[34:37], v[154:157], v[212:215], v[46:49]
	v_mfma_f32_16x16x32_bf16 v[22:25], v[146:149], v[220:223], v[22:25]
	v_mfma_f32_16x16x32_bf16 v[18:21], v[154:157], v[220:223], v[18:21]
	v_mfma_f32_16x16x32_bf16 v[6:9], v[146:149], v[228:231], v[6:9]
	v_mfma_f32_16x16x32_bf16 v[2:5], v[154:157], v[228:231], v[2:5]
	v_mfma_f32_16x16x32_bf16 v[50:53], v[184:187], v[216:219], v[34:37]
	v_mfma_f32_16x16x32_bf16 v[22:25], v[150:153], v[224:227], v[22:25]
	v_mfma_f32_16x16x32_bf16 v[18:21], v[184:187], v[224:227], v[18:21]
	v_mfma_f32_16x16x32_bf16 v[6:9], v[150:153], v[232:235], v[6:9]
	v_mfma_f32_16x16x32_bf16 v[2:5], v[184:187], v[232:235], v[2:5]
	s_setprio 0
	s_add_i32 s39, s39, 2
	s_add_u32 s6, s6, 0x100
	s_addc_u32 s7, s7, 0
	s_add_u32 s37, s37, 0x100
	s_addc_u32 s38, s38, 0
	s_cmp_gt_u32 s39, 13
	s_barrier
	s_cbranch_scc0 .LBB0_613
	s_and_b64 vcc, exec, s[54:55]
	s_cbranch_vccz .LBB0_616
	s_barrier

; #define PG8_STAGE(bufoff, gbase, voff) do { _Pragma("unroll") for (int _i = 0; _i < 2; ++_i) \
;         __builtin_amdgcn_global_load_lds((const unsigned*)((const char*)(gbase) + (voff)[_i]), (LAS unsigned*)(lds + (bufoff) + ldsw + _i * 8192), 16, 0, 0); } while (0)
; #define PG8_LDA(dst, b, h) do { _Pragma("unroll") for (int m = 0; m < 4; ++m) _Pragma("unroll") for (int k = 0; k < 2; ++k) dst[m][k] = *(const LAS bf16x8*)(lds + PG8_SA(b, h) + aoff + m * 2048 + k * 1024); } while (0)
; #define PG8_LDB(dst, b, h) do { _Pragma("unroll") for (int n = 0; n < 2; ++n) _Pragma("unroll") for (int k = 0; k < 2; ++k) dst[n][k] = *(const LAS bf16x8*)(lds + PG8_SB(b, h) + boff + n * 2048 + k * 1024); } while (0)
; #define PG8_MMA(ai, bj, At, Bt) do { __builtin_amdgcn_s_setprio(1); _Pragma("unroll") for (int m = 0; m < 4; ++m) _Pragma("unroll") for (int n = 0; n < 2; ++n) _Pragma("unroll") for (int k = 0; k < 2; ++k) \
;         acc[ai][bj][m][n] = __builtin_amdgcn_mfma_f32_16x16x32_bf16(Bt[n][k], At[m][k], acc[ai][bj][m][n], 0, 0, 0); __builtin_amdgcn_s_setprio(0); } while (0)
; #define PG8_WAIT_V(n) asm volatile("s_waitcnt vmcnt(" #n ")" ::: "memory")
; #define PG8_WAIT_L(n) asm volatile("s_waitcnt lgkmcnt(" #n ")" ::: "memory")
; #define PG8_BAR __builtin_amdgcn_s_barrier()
; #define PG8_SCHED __builtin_amdgcn_sched_barrier(0)
; template <class Epi, class Sched, bool ALIGN_EPI = false, bool SP2 = false>
; __device__ __forceinline__ void gemm_phase(LAS unsigned char* lds, const Gemm g, const Sched& S, const Epi& E, const int tid) {
;     ...
;             PG8_LDB(B0, 0, 0); PG8_LDB(B1, 0, 1); PG8_SCHED; PG8_LDA(At, 0, 0); PG8_STAGE(PG8_SA(1, 1), a1 + hstep, voffA);
;             PG8_WAIT_V(8); PG8_WAIT_L(0); PG8_BAR; PG8_MMA(0, 0, At, B0); PG8_MMA(0, 1, At, B1); PG8_BAR; PG8_SCHED;
;             PG8_LDA(At, 0, 1); PG8_STAGE(PG8_SB(0, 0), b2, voffB); PG8_STAGE(PG8_SB(0, 1), b2 + hstep, voffB); PG8_STAGE(PG8_SA(0, 0), a2, voffA);
.LBB0_1150:
	s_add_u32 s14, s4, 0xfffc0080
	s_addc_u32 s15, s5, -1
	s_add_i32 s64, 0, 0x10000
	s_cmp_eq_u32 s63, 12
	s_cselect_b32 s37, s29, s15
	s_cselect_b32 s36, s59, s14
	s_cselect_b32 s15, s27, s62
	s_cselect_b32 s14, s60, s61
	s_add_i32 s66, 0, 0x14000
	v_add_u32_e32 v142, s64, v208
	v_add_u32_e32 v158, s66, v208
	ds_read_b128 v[130:133], v142
	ds_read_b128 v[134:137], v142 offset:1024
	ds_read_b128 v[138:141], v142 offset:2048
	ds_read_b128 v[142:145], v142 offset:3072
	ds_read_b128 v[146:149], v158
	ds_read_b128 v[150:153], v158 offset:1024
	ds_read_b128 v[154:157], v158 offset:2048
	ds_read_b128 v[158:161], v158 offset:3072
	v_lshl_add_u64 v[198:199], s[4:5], 0, v[182:183]
	s_add_i32 m0, s41, 0xc000
	ds_read_b128 v[186:189], v210
	ds_read_b128 v[190:193], v210 offset:1024
	ds_read_b128 v[194:197], v210 offset:2048
	ds_read_b128 v[212:215], v210 offset:3072
	ds_read_b128 v[216:219], v210 offset:4096
	ds_read_b128 v[220:223], v210 offset:5120
	ds_read_b128 v[224:227], v210 offset:6144
	ds_read_b128 v[228:231], v210 offset:7168
	global_load_lds_dwordx4 v[198:199], off
	v_lshl_add_u64 v[198:199], s[4:5], 0, v[184:185]
	s_add_i32 m0, s41, 0xe000
	s_nop 0
	global_load_lds_dwordx4 v[198:199], off
	s_waitcnt vmcnt(8)
	s_waitcnt lgkmcnt(0)
	s_barrier
	s_setprio 1
	s_waitcnt lgkmcnt(0)
	v_mfma_f32_16x16x32_bf16 v[126:129], v[130:133], v[186:189], v[126:129]
	v_mfma_f32_16x16x32_bf16 v[122:125], v[138:141], v[186:189], v[122:125]
	v_mfma_f32_16x16x32_bf16 v[110:113], v[130:133], v[194:197], v[110:113]
	v_mfma_f32_16x16x32_bf16 v[106:109], v[138:141], v[194:197], v[106:109]
	v_mfma_f32_16x16x32_bf16 v[94:97], v[130:133], v[216:219], v[94:97]
	v_mfma_f32_16x16x32_bf16 v[90:93], v[138:141], v[216:219], v[90:93]
	v_mfma_f32_16x16x32_bf16 v[78:81], v[130:133], v[224:227], v[78:81]
	v_mfma_f32_16x16x32_bf16 v[74:77], v[138:141], v[224:227], v[74:77]
	v_mfma_f32_16x16x32_bf16 v[126:129], v[134:137], v[190:193], v[126:129]
	v_mfma_f32_16x16x32_bf16 v[122:125], v[142:145], v[190:193], v[122:125]
	v_mfma_f32_16x16x32_bf16 v[110:113], v[134:137], v[212:215], v[110:113]
	v_mfma_f32_16x16x32_bf16 v[106:109], v[142:145], v[212:215], v[106:109]
	v_mfma_f32_16x16x32_bf16 v[94:97], v[134:137], v[220:223], v[94:97]
	v_mfma_f32_16x16x32_bf16 v[90:93], v[142:145], v[220:223], v[90:93]
	v_mfma_f32_16x16x32_bf16 v[78:81], v[134:137], v[228:231], v[78:81]
	v_mfma_f32_16x16x32_bf16 v[74:77], v[142:145], v[228:231], v[74:77]
	s_setprio 0
	s_setprio 1
	v_mfma_f32_16x16x32_bf16 v[118:121], v[146:149], v[186:189], v[118:121]
	v_mfma_f32_16x16x32_bf16 v[114:117], v[154:157], v[186:189], v[114:117]
	v_mfma_f32_16x16x32_bf16 v[102:105], v[146:149], v[194:197], v[102:105]
	v_mfma_f32_16x16x32_bf16 v[98:101], v[154:157], v[194:197], v[98:101]
	v_mfma_f32_16x16x32_bf16 v[86:89], v[146:149], v[216:219], v[86:89]
	v_mfma_f32_16x16x32_bf16 v[82:85], v[154:157], v[216:219], v[82:85]
	v_mfma_f32_16x16x32_bf16 v[70:73], v[146:149], v[224:227], v[70:73]
	v_mfma_f32_16x16x32_bf16 v[66:69], v[154:157], v[224:227], v[66:69]
	v_mfma_f32_16x16x32_bf16 v[118:121], v[150:153], v[190:193], v[118:121]
	v_mfma_f32_16x16x32_bf16 v[114:117], v[158:161], v[190:193], v[114:117]
	v_mfma_f32_16x16x32_bf16 v[102:105], v[150:153], v[212:215], v[102:105]
	v_mfma_f32_16x16x32_bf16 v[98:101], v[158:161], v[212:215], v[98:101]
	v_mfma_f32_16x16x32_bf16 v[86:89], v[150:153], v[220:223], v[86:89]
	v_mfma_f32_16x16x32_bf16 v[82:85], v[158:161], v[220:223], v[82:85]
	v_mfma_f32_16x16x32_bf16 v[70:73], v[150:153], v[228:231], v[70:73]
	v_mfma_f32_16x16x32_bf16 v[66:69], v[158:161], v[228:231], v[66:69]
	s_setprio 0
	s_barrier
	s_add_i32 s64, s64, s40
	v_lshl_add_u64 v[198:199], s[14:15], 0, v[0:1]
	s_mov_b32 m0, s64
	ds_read_b128 v[186:189], v210 offset:16384
	ds_read_b128 v[190:193], v210 offset:17408
	ds_read_b128 v[194:197], v210 offset:18432
	ds_read_b128 v[212:215], v210 offset:19456
	ds_read_b128 v[216:219], v210 offset:20480
	ds_read_b128 v[220:223], v210 offset:21504
	ds_read_b128 v[224:227], v210 offset:22528
	ds_read_b128 v[228:231], v210 offset:23552
	global_load_lds_dwordx4 v[198:199], off
	s_add_i32 m0, s64, 0x2000
	s_add_u32 s64, s14, 0x40000
	v_lshl_add_u64 v[232:233], s[14:15], 0, v[174:175]
	s_addc_u32 s65, s15, 0
	s_add_i32 s66, s66, s40
	global_load_lds_dwordx4 v[232:233], off
	v_lshl_add_u64 v[234:235], s[64:65], 0, v[0:1]
	s_mov_b32 m0, s66
	v_lshl_add_u64 v[236:237], s[36:37], 0, v[176:177]
	global_load_lds_dwordx4 v[234:235], off
	v_lshl_add_u64 v[234:235], s[64:65], 0, v[174:175]
	s_add_i32 m0, s66, 0x2000
	s_nop 0
	global_load_lds_dwordx4 v[234:235], off
	v_lshl_add_u64 v[234:235], s[36:37], 0, v[178:179]
	s_mov_b32 m0, s41
	s_nop 0
	global_load_lds_dwordx4 v[234:235], off
	s_mov_b32 m0, s42
	s_nop 0
	global_load_lds_dwordx4 v[236:237], off
	s_waitcnt vmcnt(8)
	s_waitcnt lgkmcnt(0)
	s_barrier
; #define PG8_STAGE(bufoff, gbase, voff) do { _Pragma("unroll") for (int _i = 0; _i < 2; ++_i) \
;         __builtin_amdgcn_global_load_lds((const unsigned*)((const char*)(gbase) + (voff)[_i]), (LAS unsigned*)(lds + (bufoff) + ldsw + _i * 8192), 16, 0, 0); } while (0)
; #define PG8_LDA(dst, b, h) do { _Pragma("unroll") for (int m = 0; m < 4; ++m) _Pragma("unroll") for (int k = 0; k < 2; ++k) dst[m][k] = *(const LAS bf16x8*)(lds + PG8_SA(b, h) + aoff + m * 2048 + k * 1024); } while (0)
; #define PG8_LDB(dst, b, h) do { _Pragma("unroll") for (int n = 0; n < 2; ++n) _Pragma("unroll") for (int k = 0; k < 2; ++k) dst[n][k] = *(const LAS bf16x8*)(lds + PG8_SB(b, h) + boff + n * 2048 + k * 1024); } while (0)
; #define PG8_MMA(ai, bj, At, Bt) do { __builtin_amdgcn_s_setprio(1); _Pragma("unroll") for (int m = 0; m < 4; ++m) _Pragma("unroll") for (int n = 0; n < 2; ++n) _Pragma("unroll") for (int k = 0; k < 2; ++k) \
;         acc[ai][bj][m][n] = __builtin_amdgcn_mfma_f32_16x16x32_bf16(Bt[n][k], At[m][k], acc[ai][bj][m][n], 0, 0, 0); __builtin_amdgcn_s_setprio(0); } while (0)
; #define PG8_WAIT_V(n) asm volatile("s_waitcnt vmcnt(" #n ")" ::: "memory")
; #define PG8_WAIT_L(n) asm volatile("s_waitcnt lgkmcnt(" #n ")" ::: "memory")
; #define PG8_BAR __builtin_amdgcn_s_barrier()
; #define PG8_SCHED __builtin_amdgcn_sched_barrier(0)
; template <class Epi, class Sched, bool ALIGN_EPI = false, bool SP2 = false>
; __device__ __forceinline__ void gemm_phase(LAS unsigned char* lds, const Gemm g, const Sched& S, const Epi& E, const int tid) {
;     ...
;             PG8_WAIT_V(8); PG8_WAIT_L(0); PG8_BAR; PG8_MMA(1, 0, At, B0); PG8_MMA(1, 1, At, B1); PG8_BAR; PG8_SCHED;
;             PG8_LDB(B0, 1, 0); PG8_LDB(B1, 1, 1); PG8_SCHED; PG8_LDA(At, 1, 0); PG8_STAGE(PG8_SA(0, 1), a2 + hstep, voffA);
;             PG8_WAIT_V(8); PG8_WAIT_L(0); PG8_BAR; PG8_MMA(0, 0, At, B0); PG8_MMA(0, 1, At, B1); PG8_BAR; PG8_SCHED;
	s_setprio 1
	s_waitcnt lgkmcnt(0)
	v_mfma_f32_16x16x32_bf16 v[62:65], v[130:133], v[186:189], v[62:65]
	v_mfma_f32_16x16x32_bf16 v[58:61], v[138:141], v[186:189], v[58:61]
	v_mfma_f32_16x16x32_bf16 v[46:49], v[130:133], v[194:197], v[46:49]
	v_mfma_f32_16x16x32_bf16 v[42:45], v[138:141], v[194:197], v[42:45]
	v_mfma_f32_16x16x32_bf16 v[30:33], v[130:133], v[216:219], v[30:33]
	v_mfma_f32_16x16x32_bf16 v[26:29], v[138:141], v[216:219], v[26:29]
	v_mfma_f32_16x16x32_bf16 v[14:17], v[130:133], v[224:227], v[14:17]
	v_mfma_f32_16x16x32_bf16 v[10:13], v[138:141], v[224:227], v[10:13]
	v_mfma_f32_16x16x32_bf16 v[62:65], v[134:137], v[190:193], v[62:65]
	v_mfma_f32_16x16x32_bf16 v[58:61], v[142:145], v[190:193], v[58:61]
	v_mfma_f32_16x16x32_bf16 v[46:49], v[134:137], v[212:215], v[46:49]
	v_mfma_f32_16x16x32_bf16 v[42:45], v[142:145], v[212:215], v[42:45]
	v_mfma_f32_16x16x32_bf16 v[30:33], v[134:137], v[220:223], v[30:33]
	v_mfma_f32_16x16x32_bf16 v[26:29], v[142:145], v[220:223], v[26:29]
	v_mfma_f32_16x16x32_bf16 v[14:17], v[134:137], v[228:231], v[14:17]
	v_mfma_f32_16x16x32_bf16 v[10:13], v[142:145], v[228:231], v[10:13]
	s_setprio 0
	s_setprio 1
	v_mfma_f32_16x16x32_bf16 v[54:57], v[146:149], v[186:189], v[54:57]
	v_mfma_f32_16x16x32_bf16 v[50:53], v[154:157], v[186:189], v[50:53]
	v_mfma_f32_16x16x32_bf16 v[38:41], v[146:149], v[194:197], v[38:41]
	v_mfma_f32_16x16x32_bf16 v[34:37], v[154:157], v[194:197], v[34:37]
	v_mfma_f32_16x16x32_bf16 v[22:25], v[146:149], v[216:219], v[22:25]
	v_mfma_f32_16x16x32_bf16 v[18:21], v[154:157], v[216:219], v[18:21]
	v_mfma_f32_16x16x32_bf16 v[6:9], v[146:149], v[224:227], v[6:9]
	v_mfma_f32_16x16x32_bf16 v[2:5], v[154:157], v[224:227], v[2:5]
	v_mfma_f32_16x16x32_bf16 v[54:57], v[150:153], v[190:193], v[54:57]
	v_mfma_f32_16x16x32_bf16 v[50:53], v[158:161], v[190:193], v[50:53]
	v_mfma_f32_16x16x32_bf16 v[38:41], v[150:153], v[212:215], v[38:41]
	v_mfma_f32_16x16x32_bf16 v[34:37], v[158:161], v[212:215], v[34:37]
	v_mfma_f32_16x16x32_bf16 v[22:25], v[150:153], v[220:223], v[22:25]
	v_mfma_f32_16x16x32_bf16 v[18:21], v[158:161], v[220:223], v[18:21]
	v_mfma_f32_16x16x32_bf16 v[6:9], v[150:153], v[228:231], v[6:9]
	v_mfma_f32_16x16x32_bf16 v[2:5], v[158:161], v[228:231], v[2:5]
	s_setprio 0
	s_barrier
	s_add_i32 s64, 0, 0x18000
	v_add_u32_e32 v142, s64, v208
	v_add_u32_e32 v158, s93, v208
	ds_read_b128 v[130:133], v142
	ds_read_b128 v[134:137], v142 offset:1024
	ds_read_b128 v[138:141], v142 offset:2048
	ds_read_b128 v[142:145], v142 offset:3072
	ds_read_b128 v[146:149], v158
	ds_read_b128 v[150:153], v158 offset:1024
	ds_read_b128 v[154:157], v158 offset:2048
	ds_read_b128 v[158:161], v158 offset:3072
	s_add_u32 s36, s36, 0x40000
	s_addc_u32 s37, s37, 0
	s_mov_b32 m0, s43
	v_lshl_add_u64 v[238:239], s[36:37], 0, v[178:179]
	ds_read_b128 v[186:189], v210 offset:32768
	ds_read_b128 v[190:193], v210 offset:33792
	ds_read_b128 v[194:197], v210 offset:34816
	ds_read_b128 v[212:215], v210 offset:35840
	ds_read_b128 v[216:219], v210 offset:36864
	ds_read_b128 v[220:223], v210 offset:37888
	ds_read_b128 v[224:227], v210 offset:38912
	ds_read_b128 v[228:231], v210 offset:39936
	global_load_lds_dwordx4 v[238:239], off
	v_lshl_add_u64 v[238:239], s[36:37], 0, v[176:177]
	s_mov_b32 m0, s44
	s_nop 0
	global_load_lds_dwordx4 v[238:239], off
	s_waitcnt vmcnt(8)
	s_waitcnt lgkmcnt(0)
	s_barrier
	s_setprio 1
	s_waitcnt lgkmcnt(0)
	v_mfma_f32_16x16x32_bf16 v[126:129], v[130:133], v[186:189], v[126:129]
	v_mfma_f32_16x16x32_bf16 v[122:125], v[138:141], v[186:189], v[122:125]
	v_mfma_f32_16x16x32_bf16 v[110:113], v[130:133], v[194:197], v[110:113]
	v_mfma_f32_16x16x32_bf16 v[106:109], v[138:141], v[194:197], v[106:109]
	v_mfma_f32_16x16x32_bf16 v[94:97], v[130:133], v[216:219], v[94:97]
	v_mfma_f32_16x16x32_bf16 v[90:93], v[138:141], v[216:219], v[90:93]
	v_mfma_f32_16x16x32_bf16 v[78:81], v[130:133], v[224:227], v[78:81]
	v_mfma_f32_16x16x32_bf16 v[74:77], v[138:141], v[224:227], v[74:77]
	v_mfma_f32_16x16x32_bf16 v[126:129], v[134:137], v[190:193], v[126:129]
	v_mfma_f32_16x16x32_bf16 v[122:125], v[142:145], v[190:193], v[122:125]
	v_mfma_f32_16x16x32_bf16 v[110:113], v[134:137], v[212:215], v[110:113]
	v_mfma_f32_16x16x32_bf16 v[106:109], v[142:145], v[212:215], v[106:109]
	v_mfma_f32_16x16x32_bf16 v[94:97], v[134:137], v[220:223], v[94:97]
	v_mfma_f32_16x16x32_bf16 v[90:93], v[142:145], v[220:223], v[90:93]
	v_mfma_f32_16x16x32_bf16 v[78:81], v[134:137], v[228:231], v[78:81]
	v_mfma_f32_16x16x32_bf16 v[74:77], v[142:145], v[228:231], v[74:77]
	s_setprio 0
	s_setprio 1
	v_mfma_f32_16x16x32_bf16 v[118:121], v[146:149], v[186:189], v[118:121]
	v_mfma_f32_16x16x32_bf16 v[114:117], v[154:157], v[186:189], v[114:117]
	v_mfma_f32_16x16x32_bf16 v[102:105], v[146:149], v[194:197], v[102:105]
	v_mfma_f32_16x16x32_bf16 v[98:101], v[154:157], v[194:197], v[98:101]
	v_mfma_f32_16x16x32_bf16 v[86:89], v[146:149], v[216:219], v[86:89]
	v_mfma_f32_16x16x32_bf16 v[82:85], v[154:157], v[216:219], v[82:85]
	v_mfma_f32_16x16x32_bf16 v[70:73], v[146:149], v[224:227], v[70:73]
	v_mfma_f32_16x16x32_bf16 v[66:69], v[154:157], v[224:227], v[66:69]
	v_mfma_f32_16x16x32_bf16 v[118:121], v[150:153], v[190:193], v[118:121]
	v_mfma_f32_16x16x32_bf16 v[114:117], v[158:161], v[190:193], v[114:117]
	v_mfma_f32_16x16x32_bf16 v[102:105], v[150:153], v[212:215], v[102:105]
	v_mfma_f32_16x16x32_bf16 v[98:101], v[158:161], v[212:215], v[98:101]
	v_mfma_f32_16x16x32_bf16 v[86:89], v[150:153], v[220:223], v[86:89]
	v_mfma_f32_16x16x32_bf16 v[82:85], v[158:161], v[220:223], v[82:85]
	v_mfma_f32_16x16x32_bf16 v[70:73], v[150:153], v[228:231], v[70:73]
	v_mfma_f32_16x16x32_bf16 v[66:69], v[158:161], v[228:231], v[66:69]
	s_setprio 0
	s_barrier
; #define PG8_STAGE(bufoff, gbase, voff) do { _Pragma("unroll") for (int _i = 0; _i < 2; ++_i) \
;         __builtin_amdgcn_global_load_lds((const unsigned*)((const char*)(gbase) + (voff)[_i]), (LAS unsigned*)(lds + (bufoff) + ldsw + _i * 8192), 16, 0, 0); } while (0)
; #define PG8_LDA(dst, b, h) do { _Pragma("unroll") for (int m = 0; m < 4; ++m) _Pragma("unroll") for (int k = 0; k < 2; ++k) dst[m][k] = *(const LAS bf16x8*)(lds + PG8_SA(b, h) + aoff + m * 2048 + k * 1024); } while (0)
; #define PG8_MMA(ai, bj, At, Bt) do { __builtin_amdgcn_s_setprio(1); _Pragma("unroll") for (int m = 0; m < 4; ++m) _Pragma("unroll") for (int n = 0; n < 2; ++n) _Pragma("unroll") for (int k = 0; k < 2; ++k) \
;         acc[ai][bj][m][n] = __builtin_amdgcn_mfma_f32_16x16x32_bf16(Bt[n][k], At[m][k], acc[ai][bj][m][n], 0, 0, 0); __builtin_amdgcn_s_setprio(0); } while (0)
; #define PG8_WAIT_V(n) asm volatile("s_waitcnt vmcnt(" #n ")" ::: "memory")
; #define PG8_WAIT_L(n) asm volatile("s_waitcnt lgkmcnt(" #n ")" ::: "memory")
; #define PG8_BAR __builtin_amdgcn_s_barrier()
; #define PG8_SCHED __builtin_amdgcn_sched_barrier(0)
; template <class Epi, class Sched, bool ALIGN_EPI = false, bool SP2 = false>
; __device__ __forceinline__ void gemm_phase(LAS unsigned char* lds, const Gemm g, const Sched& S, const Epi& E, const int tid) {
;     ...
;         for (int t = 0; t < nt; t += 2) {
;             const bool last = (t == nt - 2);
;             const char* a1 = cA + (size_t)(t + 1) * kstep;
;             const char* a2 = last ? nA : cA + (size_t)(t + 2) * kstep; const char* b2 = last ? nB : cB + (size_t)(t + 2) * kstep;
;             const char* a3 = a2 + kstep; const char* b3 = b2 + kstep;
;     ...
;             PG8_LDA(At, 1, 1); PG8_STAGE(PG8_SB(1, 0), b3, voffB); PG8_STAGE(PG8_SB(1, 1), b3 + hstep, voffB); PG8_STAGE(PG8_SA(1, 0), a3, voffA);
;             PG8_WAIT_V(8); PG8_WAIT_L(0); PG8_BAR; PG8_MMA(1, 0, At, B0); PG8_MMA(1, 1, At, B1); PG8_BAR; PG8_SCHED;
	s_add_i32 s36, s64, s40
	v_lshl_add_u64 v[198:199], v[198:199], 0, s[0:1]
	s_mov_b32 m0, s36
	ds_read_b128 v[186:189], v210 offset:49152
	ds_read_b128 v[190:193], v210 offset:50176
	ds_read_b128 v[194:197], v210 offset:51200
	ds_read_b128 v[212:215], v210 offset:52224
	ds_read_b128 v[216:219], v210 offset:53248
	ds_read_b128 v[220:223], v210 offset:54272
	ds_read_b128 v[224:227], v210 offset:55296
	ds_read_b128 v[228:231], v210 offset:56320
	global_load_lds_dwordx4 v[198:199], off
	s_add_i32 m0, s36, 0x2000
	s_add_u32 s14, s14, 0x40080
	v_lshl_add_u64 v[198:199], v[232:233], 0, s[0:1]
	s_addc_u32 s15, s15, 0
	s_add_i32 s36, s93, s40
	global_load_lds_dwordx4 v[198:199], off
	v_lshl_add_u64 v[198:199], s[14:15], 0, v[0:1]
	s_mov_b32 m0, s36
	s_nop 0
	global_load_lds_dwordx4 v[198:199], off
	v_lshl_add_u64 v[198:199], s[14:15], 0, v[174:175]
	s_add_i32 m0, s36, 0x2000
	s_nop 0
	global_load_lds_dwordx4 v[198:199], off
	v_lshl_add_u64 v[198:199], v[234:235], 0, s[0:1]
	s_mov_b32 m0, s45
	s_nop 0
	global_load_lds_dwordx4 v[198:199], off
	v_lshl_add_u64 v[198:199], v[236:237], 0, s[0:1]
	s_mov_b32 m0, s46
	s_nop 0
	global_load_lds_dwordx4 v[198:199], off
	s_waitcnt vmcnt(8)
	s_waitcnt lgkmcnt(0)
	s_barrier
	s_setprio 1
	s_waitcnt lgkmcnt(0)
	v_mfma_f32_16x16x32_bf16 v[62:65], v[130:133], v[186:189], v[62:65]
	v_mfma_f32_16x16x32_bf16 v[58:61], v[138:141], v[186:189], v[58:61]
	v_mfma_f32_16x16x32_bf16 v[46:49], v[130:133], v[194:197], v[46:49]
	v_mfma_f32_16x16x32_bf16 v[42:45], v[138:141], v[194:197], v[42:45]
	v_mfma_f32_16x16x32_bf16 v[30:33], v[130:133], v[216:219], v[30:33]
	v_mfma_f32_16x16x32_bf16 v[26:29], v[138:141], v[216:219], v[26:29]
	v_mfma_f32_16x16x32_bf16 v[14:17], v[130:133], v[224:227], v[14:17]
	v_mfma_f32_16x16x32_bf16 v[10:13], v[138:141], v[224:227], v[10:13]
	v_mfma_f32_16x16x32_bf16 v[62:65], v[134:137], v[190:193], v[62:65]
	v_mfma_f32_16x16x32_bf16 v[58:61], v[142:145], v[190:193], v[58:61]
	v_mfma_f32_16x16x32_bf16 v[46:49], v[134:137], v[212:215], v[46:49]
	v_mfma_f32_16x16x32_bf16 v[42:45], v[142:145], v[212:215], v[42:45]
	v_mfma_f32_16x16x32_bf16 v[30:33], v[134:137], v[220:223], v[30:33]
	v_mfma_f32_16x16x32_bf16 v[26:29], v[142:145], v[220:223], v[26:29]
	v_mfma_f32_16x16x32_bf16 v[14:17], v[134:137], v[228:231], v[14:17]
	v_mfma_f32_16x16x32_bf16 v[10:13], v[142:145], v[228:231], v[10:13]
	s_setprio 0
	s_setprio 1
	v_mfma_f32_16x16x32_bf16 v[54:57], v[146:149], v[186:189], v[54:57]
	v_mfma_f32_16x16x32_bf16 v[50:53], v[154:157], v[186:189], v[50:53]
	v_mfma_f32_16x16x32_bf16 v[38:41], v[146:149], v[194:197], v[38:41]
	v_mfma_f32_16x16x32_bf16 v[34:37], v[154:157], v[194:197], v[34:37]
	v_mfma_f32_16x16x32_bf16 v[22:25], v[146:149], v[216:219], v[22:25]
	v_mfma_f32_16x16x32_bf16 v[18:21], v[154:157], v[216:219], v[18:21]
	v_mfma_f32_16x16x32_bf16 v[6:9], v[146:149], v[224:227], v[6:9]
	v_mfma_f32_16x16x32_bf16 v[2:5], v[154:157], v[224:227], v[2:5]
	v_mfma_f32_16x16x32_bf16 v[54:57], v[150:153], v[190:193], v[54:57]
	v_mfma_f32_16x16x32_bf16 v[50:53], v[158:161], v[190:193], v[50:53]
	v_mfma_f32_16x16x32_bf16 v[38:41], v[150:153], v[212:215], v[38:41]
	v_mfma_f32_16x16x32_bf16 v[34:37], v[158:161], v[212:215], v[34:37]
	v_mfma_f32_16x16x32_bf16 v[22:25], v[150:153], v[220:223], v[22:25]
	v_mfma_f32_16x16x32_bf16 v[18:21], v[158:161], v[220:223], v[18:21]
	v_mfma_f32_16x16x32_bf16 v[6:9], v[150:153], v[228:231], v[6:9]
	v_mfma_f32_16x16x32_bf16 v[2:5], v[158:161], v[228:231], v[2:5]
	s_setprio 0
	s_add_i32 s63, s63, 2
	s_add_u32 s4, s4, 0x100
	s_addc_u32 s5, s5, 0
	s_add_u32 s61, s61, 0x100
	s_addc_u32 s62, s62, 0
	s_cmp_gt_u32 s63, 13
	s_barrier
	s_cbranch_scc0 .LBB0_1150
	s_and_b64 vcc, exec, s[22:23]
	s_cbranch_vccz .LBB0_1153
	s_barrier

; #define PG8_STAGE(bufoff, gbase, voff) do { _Pragma("unroll") for (int _i = 0; _i < 2; ++_i) \
;         __builtin_amdgcn_global_load_lds((const unsigned*)((const char*)(gbase) + (voff)[_i]), (LAS unsigned*)(lds + (bufoff) + ldsw + _i * 8192), 16, 0, 0); } while (0)
; #define PG8_LDA(dst, b, h) do { _Pragma("unroll") for (int m = 0; m < 4; ++m) _Pragma("unroll") for (int k = 0; k < 2; ++k) dst[m][k] = *(const LAS bf16x8*)(lds + PG8_SA(b, h) + aoff + m * 2048 + k * 1024); } while (0)
; #define PG8_LDB(dst, b, h) do { _Pragma("unroll") for (int n = 0; n < 2; ++n) _Pragma("unroll") for (int k = 0; k < 2; ++k) dst[n][k] = *(const LAS bf16x8*)(lds + PG8_SB(b, h) + boff + n * 2048 + k * 1024); } while (0)
; #define PG8_MMA(ai, bj, At, Bt) do { __builtin_amdgcn_s_setprio(1); _Pragma("unroll") for (int m = 0; m < 4; ++m) _Pragma("unroll") for (int n = 0; n < 2; ++n) _Pragma("unroll") for (int k = 0; k < 2; ++k) \
;         acc[ai][bj][m][n] = __builtin_amdgcn_mfma_f32_16x16x32_bf16(Bt[n][k], At[m][k], acc[ai][bj][m][n], 0, 0, 0); __builtin_amdgcn_s_setprio(0); } while (0)
; #define PG8_WAIT_V(n) asm volatile("s_waitcnt vmcnt(" #n ")" ::: "memory")
; #define PG8_WAIT_L(n) asm volatile("s_waitcnt lgkmcnt(" #n ")" ::: "memory")
; #define PG8_BAR __builtin_amdgcn_s_barrier()
; #define PG8_SCHED __builtin_amdgcn_sched_barrier(0)
; template <class Epi, class Sched, bool ALIGN_EPI = false, bool SP2 = false>
; __device__ __forceinline__ void gemm_phase(LAS unsigned char* lds, const Gemm g, const Sched& S, const Epi& E, const int tid) {
;     ...
;             PG8_LDB(B0, 0, 0); PG8_LDB(B1, 0, 1); PG8_SCHED; PG8_LDA(At, 0, 0); PG8_STAGE(PG8_SA(1, 1), a1 + hstep, voffA);
;             PG8_WAIT_V(8); PG8_WAIT_L(0); PG8_BAR; PG8_MMA(0, 0, At, B0); PG8_MMA(0, 1, At, B1); PG8_BAR; PG8_SCHED;
;             PG8_LDA(At, 0, 1); PG8_STAGE(PG8_SB(0, 0), b2, voffB); PG8_STAGE(PG8_SB(0, 1), b2 + hstep, voffB); PG8_STAGE(PG8_SA(0, 0), a2, voffA);
.LBB0_1282:
	s_add_u32 s26, s24, 0xfffc0080
	s_addc_u32 s27, s25, -1
	s_add_i32 s49, 0, 0x10000
	s_cmp_eq_u32 s48, 12
	s_cselect_b32 s29, s19, s27
	s_cselect_b32 s28, s44, s26
	s_cselect_b32 s27, s15, s47
	s_cselect_b32 s26, s45, s46
	s_add_i32 s59, 0, 0x14000
	v_add_u32_e32 v156, s49, v153
	v_add_u32_e32 v160, s59, v153
	ds_read_b128 v[140:143], v156
	ds_read_b128 v[144:147], v156 offset:1024
	ds_read_b128 v[148:151], v156 offset:2048
	ds_read_b128 v[156:159], v156 offset:3072
	ds_read_b128 v[174:177], v160
	ds_read_b128 v[178:181], v160 offset:1024
	ds_read_b128 v[182:185], v160 offset:2048
	ds_read_b128 v[186:189], v160 offset:3072
	v_lshl_add_u64 v[160:161], s[24:25], 0, v[136:137]
	s_add_i32 m0, s35, 0xc000
	ds_read_b128 v[190:193], v155
	ds_read_b128 v[194:197], v155 offset:1024
	ds_read_b128 v[208:211], v155 offset:2048
	ds_read_b128 v[212:215], v155 offset:3072
	ds_read_b128 v[216:219], v155 offset:4096
	ds_read_b128 v[220:223], v155 offset:5120
	ds_read_b128 v[224:227], v155 offset:6144
	ds_read_b128 v[228:231], v155 offset:7168
	global_load_lds_dwordx4 v[160:161], off
	v_lshl_add_u64 v[160:161], s[24:25], 0, v[138:139]
	s_add_i32 m0, s35, 0xe000
	s_nop 0
	global_load_lds_dwordx4 v[160:161], off
	s_waitcnt vmcnt(8)
	s_waitcnt lgkmcnt(0)
	s_barrier
	s_setprio 1
	s_waitcnt lgkmcnt(0)
	v_mfma_f32_16x16x32_bf16 v[126:129], v[140:143], v[190:193], v[126:129]
	v_mfma_f32_16x16x32_bf16 v[122:125], v[148:151], v[190:193], v[122:125]
	v_mfma_f32_16x16x32_bf16 v[110:113], v[140:143], v[208:211], v[110:113]
	v_mfma_f32_16x16x32_bf16 v[106:109], v[148:151], v[208:211], v[106:109]
	v_mfma_f32_16x16x32_bf16 v[94:97], v[140:143], v[216:219], v[94:97]
	v_mfma_f32_16x16x32_bf16 v[90:93], v[148:151], v[216:219], v[90:93]
	v_mfma_f32_16x16x32_bf16 v[78:81], v[140:143], v[224:227], v[78:81]
	v_mfma_f32_16x16x32_bf16 v[74:77], v[148:151], v[224:227], v[74:77]
	v_mfma_f32_16x16x32_bf16 v[126:129], v[144:147], v[194:197], v[126:129]
	v_mfma_f32_16x16x32_bf16 v[122:125], v[156:159], v[194:197], v[122:125]
	v_mfma_f32_16x16x32_bf16 v[110:113], v[144:147], v[212:215], v[110:113]
	v_mfma_f32_16x16x32_bf16 v[106:109], v[156:159], v[212:215], v[106:109]
	v_mfma_f32_16x16x32_bf16 v[94:97], v[144:147], v[220:223], v[94:97]
	v_mfma_f32_16x16x32_bf16 v[90:93], v[156:159], v[220:223], v[90:93]
	v_mfma_f32_16x16x32_bf16 v[78:81], v[144:147], v[228:231], v[78:81]
	v_mfma_f32_16x16x32_bf16 v[74:77], v[156:159], v[228:231], v[74:77]
	s_setprio 0
	s_setprio 1
	v_mfma_f32_16x16x32_bf16 v[118:121], v[174:177], v[190:193], v[118:121]
	v_mfma_f32_16x16x32_bf16 v[114:117], v[182:185], v[190:193], v[114:117]
	v_mfma_f32_16x16x32_bf16 v[102:105], v[174:177], v[208:211], v[102:105]
	v_mfma_f32_16x16x32_bf16 v[98:101], v[182:185], v[208:211], v[98:101]
	v_mfma_f32_16x16x32_bf16 v[86:89], v[174:177], v[216:219], v[86:89]
	v_mfma_f32_16x16x32_bf16 v[82:85], v[182:185], v[216:219], v[82:85]
	v_mfma_f32_16x16x32_bf16 v[70:73], v[174:177], v[224:227], v[70:73]
	v_mfma_f32_16x16x32_bf16 v[66:69], v[182:185], v[224:227], v[66:69]
	v_mfma_f32_16x16x32_bf16 v[118:121], v[178:181], v[194:197], v[118:121]
	v_mfma_f32_16x16x32_bf16 v[114:117], v[186:189], v[194:197], v[114:117]
	v_mfma_f32_16x16x32_bf16 v[102:105], v[178:181], v[212:215], v[102:105]
	v_mfma_f32_16x16x32_bf16 v[98:101], v[186:189], v[212:215], v[98:101]
	v_mfma_f32_16x16x32_bf16 v[86:89], v[178:181], v[220:223], v[86:89]
	v_mfma_f32_16x16x32_bf16 v[82:85], v[186:189], v[220:223], v[82:85]
	v_mfma_f32_16x16x32_bf16 v[70:73], v[178:181], v[228:231], v[70:73]
	v_mfma_f32_16x16x32_bf16 v[66:69], v[186:189], v[228:231], v[66:69]
	s_setprio 0
	s_barrier
	s_add_i32 s49, s49, s34
	v_lshl_add_u64 v[160:161], s[26:27], 0, v[0:1]
	s_mov_b32 m0, s49
	ds_read_b128 v[190:193], v155 offset:16384
	ds_read_b128 v[194:197], v155 offset:17408
	ds_read_b128 v[208:211], v155 offset:18432
	ds_read_b128 v[212:215], v155 offset:19456
	ds_read_b128 v[216:219], v155 offset:20480
	ds_read_b128 v[220:223], v155 offset:21504
	ds_read_b128 v[224:227], v155 offset:22528
	ds_read_b128 v[228:231], v155 offset:23552
	global_load_lds_dwordx4 v[160:161], off
	s_add_i32 m0, s49, 0x2000
	s_add_u32 s60, s26, 0x40000
	v_lshl_add_u64 v[198:199], s[26:27], 0, v[130:131]
	s_addc_u32 s61, s27, 0
	s_add_i32 s49, s59, s34
	global_load_lds_dwordx4 v[198:199], off
	v_lshl_add_u64 v[232:233], s[60:61], 0, v[0:1]
	s_mov_b32 m0, s49
	v_lshl_add_u64 v[234:235], s[28:29], 0, v[132:133]
	global_load_lds_dwordx4 v[232:233], off
	v_lshl_add_u64 v[232:233], s[60:61], 0, v[130:131]
	s_add_i32 m0, s49, 0x2000
	s_nop 0
	global_load_lds_dwordx4 v[232:233], off
	v_lshl_add_u64 v[232:233], s[28:29], 0, v[134:135]
	s_mov_b32 m0, s35
	s_nop 0
	global_load_lds_dwordx4 v[232:233], off
	s_mov_b32 m0, s36
	s_nop 0
	global_load_lds_dwordx4 v[234:235], off
	s_waitcnt vmcnt(8)
	s_waitcnt lgkmcnt(0)
	s_barrier
; #define PG8_STAGE(bufoff, gbase, voff) do { _Pragma("unroll") for (int _i = 0; _i < 2; ++_i) \
;         __builtin_amdgcn_global_load_lds((const unsigned*)((const char*)(gbase) + (voff)[_i]), (LAS unsigned*)(lds + (bufoff) + ldsw + _i * 8192), 16, 0, 0); } while (0)
; #define PG8_LDA(dst, b, h) do { _Pragma("unroll") for (int m = 0; m < 4; ++m) _Pragma("unroll") for (int k = 0; k < 2; ++k) dst[m][k] = *(const LAS bf16x8*)(lds + PG8_SA(b, h) + aoff + m * 2048 + k * 1024); } while (0)
; #define PG8_LDB(dst, b, h) do { _Pragma("unroll") for (int n = 0; n < 2; ++n) _Pragma("unroll") for (int k = 0; k < 2; ++k) dst[n][k] = *(const LAS bf16x8*)(lds + PG8_SB(b, h) + boff + n * 2048 + k * 1024); } while (0)
; #define PG8_MMA(ai, bj, At, Bt) do { __builtin_amdgcn_s_setprio(1); _Pragma("unroll") for (int m = 0; m < 4; ++m) _Pragma("unroll") for (int n = 0; n < 2; ++n) _Pragma("unroll") for (int k = 0; k < 2; ++k) \
;         acc[ai][bj][m][n] = __builtin_amdgcn_mfma_f32_16x16x32_bf16(Bt[n][k], At[m][k], acc[ai][bj][m][n], 0, 0, 0); __builtin_amdgcn_s_setprio(0); } while (0)
; #define PG8_WAIT_V(n) asm volatile("s_waitcnt vmcnt(" #n ")" ::: "memory")
; #define PG8_WAIT_L(n) asm volatile("s_waitcnt lgkmcnt(" #n ")" ::: "memory")
; #define PG8_BAR __builtin_amdgcn_s_barrier()
; #define PG8_SCHED __builtin_amdgcn_sched_barrier(0)
; template <class Epi, class Sched, bool ALIGN_EPI = false, bool SP2 = false>
; __device__ __forceinline__ void gemm_phase(LAS unsigned char* lds, const Gemm g, const Sched& S, const Epi& E, const int tid) {
;     ...
;             PG8_WAIT_V(8); PG8_WAIT_L(0); PG8_BAR; PG8_MMA(1, 0, At, B0); PG8_MMA(1, 1, At, B1); PG8_BAR; PG8_SCHED;
;             PG8_LDB(B0, 1, 0); PG8_LDB(B1, 1, 1); PG8_SCHED; PG8_LDA(At, 1, 0); PG8_STAGE(PG8_SA(0, 1), a2 + hstep, voffA);
;             PG8_WAIT_V(8); PG8_WAIT_L(0); PG8_BAR; PG8_MMA(0, 0, At, B0); PG8_MMA(0, 1, At, B1); PG8_BAR; PG8_SCHED;
	s_setprio 1
	s_waitcnt lgkmcnt(0)
	v_mfma_f32_16x16x32_bf16 v[62:65], v[140:143], v[190:193], v[62:65]
	v_mfma_f32_16x16x32_bf16 v[58:61], v[148:151], v[190:193], v[58:61]
	v_mfma_f32_16x16x32_bf16 v[46:49], v[140:143], v[208:211], v[46:49]
	v_mfma_f32_16x16x32_bf16 v[42:45], v[148:151], v[208:211], v[42:45]
	v_mfma_f32_16x16x32_bf16 v[30:33], v[140:143], v[216:219], v[30:33]
	v_mfma_f32_16x16x32_bf16 v[26:29], v[148:151], v[216:219], v[26:29]
	v_mfma_f32_16x16x32_bf16 v[14:17], v[140:143], v[224:227], v[14:17]
	v_mfma_f32_16x16x32_bf16 v[10:13], v[148:151], v[224:227], v[10:13]
	v_mfma_f32_16x16x32_bf16 v[62:65], v[144:147], v[194:197], v[62:65]
	v_mfma_f32_16x16x32_bf16 v[58:61], v[156:159], v[194:197], v[58:61]
	v_mfma_f32_16x16x32_bf16 v[46:49], v[144:147], v[212:215], v[46:49]
	v_mfma_f32_16x16x32_bf16 v[42:45], v[156:159], v[212:215], v[42:45]
	v_mfma_f32_16x16x32_bf16 v[30:33], v[144:147], v[220:223], v[30:33]
	v_mfma_f32_16x16x32_bf16 v[26:29], v[156:159], v[220:223], v[26:29]
	v_mfma_f32_16x16x32_bf16 v[14:17], v[144:147], v[228:231], v[14:17]
	v_mfma_f32_16x16x32_bf16 v[10:13], v[156:159], v[228:231], v[10:13]
	s_setprio 0
	s_setprio 1
	v_mfma_f32_16x16x32_bf16 v[54:57], v[174:177], v[190:193], v[54:57]
	v_mfma_f32_16x16x32_bf16 v[50:53], v[182:185], v[190:193], v[50:53]
	v_mfma_f32_16x16x32_bf16 v[38:41], v[174:177], v[208:211], v[38:41]
	v_mfma_f32_16x16x32_bf16 v[34:37], v[182:185], v[208:211], v[34:37]
	v_mfma_f32_16x16x32_bf16 v[22:25], v[174:177], v[216:219], v[22:25]
	v_mfma_f32_16x16x32_bf16 v[18:21], v[182:185], v[216:219], v[18:21]
	v_mfma_f32_16x16x32_bf16 v[6:9], v[174:177], v[224:227], v[6:9]
	v_mfma_f32_16x16x32_bf16 v[2:5], v[182:185], v[224:227], v[2:5]
	v_mfma_f32_16x16x32_bf16 v[54:57], v[178:181], v[194:197], v[54:57]
	v_mfma_f32_16x16x32_bf16 v[50:53], v[186:189], v[194:197], v[50:53]
	v_mfma_f32_16x16x32_bf16 v[38:41], v[178:181], v[212:215], v[38:41]
	v_mfma_f32_16x16x32_bf16 v[34:37], v[186:189], v[212:215], v[34:37]
	v_mfma_f32_16x16x32_bf16 v[22:25], v[178:181], v[220:223], v[22:25]
	v_mfma_f32_16x16x32_bf16 v[18:21], v[186:189], v[220:223], v[18:21]
	v_mfma_f32_16x16x32_bf16 v[6:9], v[178:181], v[228:231], v[6:9]
	v_mfma_f32_16x16x32_bf16 v[2:5], v[186:189], v[228:231], v[2:5]
	s_setprio 0
	s_barrier
	s_add_i32 s49, 0, 0x18000
	v_add_u32_e32 v156, s49, v153
	v_add_u32_e32 v186, s93, v153
	ds_read_b128 v[140:143], v156
	ds_read_b128 v[144:147], v156 offset:1024
	ds_read_b128 v[148:151], v156 offset:2048
	ds_read_b128 v[156:159], v156 offset:3072
	ds_read_b128 v[174:177], v186
	ds_read_b128 v[178:181], v186 offset:1024
	ds_read_b128 v[182:185], v186 offset:2048
	ds_read_b128 v[186:189], v186 offset:3072
	s_add_u32 s28, s28, 0x40000
	s_addc_u32 s29, s29, 0
	s_mov_b32 m0, s37
	v_lshl_add_u64 v[236:237], s[28:29], 0, v[134:135]
	ds_read_b128 v[190:193], v155 offset:32768
	ds_read_b128 v[194:197], v155 offset:33792
	ds_read_b128 v[208:211], v155 offset:34816
	ds_read_b128 v[212:215], v155 offset:35840
	ds_read_b128 v[216:219], v155 offset:36864
	ds_read_b128 v[220:223], v155 offset:37888
	ds_read_b128 v[224:227], v155 offset:38912
	ds_read_b128 v[228:231], v155 offset:39936
	global_load_lds_dwordx4 v[236:237], off
	v_lshl_add_u64 v[236:237], s[28:29], 0, v[132:133]
	s_mov_b32 m0, s38
	s_nop 0
	global_load_lds_dwordx4 v[236:237], off
	s_waitcnt vmcnt(8)
	s_waitcnt lgkmcnt(0)
	s_barrier
	s_setprio 1
	s_waitcnt lgkmcnt(0)
	v_mfma_f32_16x16x32_bf16 v[126:129], v[140:143], v[190:193], v[126:129]
	v_mfma_f32_16x16x32_bf16 v[122:125], v[148:151], v[190:193], v[122:125]
	v_mfma_f32_16x16x32_bf16 v[110:113], v[140:143], v[208:211], v[110:113]
	v_mfma_f32_16x16x32_bf16 v[106:109], v[148:151], v[208:211], v[106:109]
	v_mfma_f32_16x16x32_bf16 v[94:97], v[140:143], v[216:219], v[94:97]
	v_mfma_f32_16x16x32_bf16 v[90:93], v[148:151], v[216:219], v[90:93]
	v_mfma_f32_16x16x32_bf16 v[78:81], v[140:143], v[224:227], v[78:81]
	v_mfma_f32_16x16x32_bf16 v[74:77], v[148:151], v[224:227], v[74:77]
	v_mfma_f32_16x16x32_bf16 v[126:129], v[144:147], v[194:197], v[126:129]
	v_mfma_f32_16x16x32_bf16 v[122:125], v[156:159], v[194:197], v[122:125]
	v_mfma_f32_16x16x32_bf16 v[110:113], v[144:147], v[212:215], v[110:113]
	v_mfma_f32_16x16x32_bf16 v[106:109], v[156:159], v[212:215], v[106:109]
	v_mfma_f32_16x16x32_bf16 v[94:97], v[144:147], v[220:223], v[94:97]
	v_mfma_f32_16x16x32_bf16 v[90:93], v[156:159], v[220:223], v[90:93]
	v_mfma_f32_16x16x32_bf16 v[78:81], v[144:147], v[228:231], v[78:81]
	v_mfma_f32_16x16x32_bf16 v[74:77], v[156:159], v[228:231], v[74:77]
	s_setprio 0
	s_setprio 1
	v_mfma_f32_16x16x32_bf16 v[118:121], v[174:177], v[190:193], v[118:121]
	v_mfma_f32_16x16x32_bf16 v[114:117], v[182:185], v[190:193], v[114:117]
	v_mfma_f32_16x16x32_bf16 v[102:105], v[174:177], v[208:211], v[102:105]
	v_mfma_f32_16x16x32_bf16 v[98:101], v[182:185], v[208:211], v[98:101]
	v_mfma_f32_16x16x32_bf16 v[86:89], v[174:177], v[216:219], v[86:89]
	v_mfma_f32_16x16x32_bf16 v[82:85], v[182:185], v[216:219], v[82:85]
	v_mfma_f32_16x16x32_bf16 v[70:73], v[174:177], v[224:227], v[70:73]
	v_mfma_f32_16x16x32_bf16 v[66:69], v[182:185], v[224:227], v[66:69]
	v_mfma_f32_16x16x32_bf16 v[118:121], v[178:181], v[194:197], v[118:121]
	v_mfma_f32_16x16x32_bf16 v[114:117], v[186:189], v[194:197], v[114:117]
	v_mfma_f32_16x16x32_bf16 v[102:105], v[178:181], v[212:215], v[102:105]
	v_mfma_f32_16x16x32_bf16 v[98:101], v[186:189], v[212:215], v[98:101]
	v_mfma_f32_16x16x32_bf16 v[86:89], v[178:181], v[220:223], v[86:89]
	v_mfma_f32_16x16x32_bf16 v[82:85], v[186:189], v[220:223], v[82:85]
	v_mfma_f32_16x16x32_bf16 v[70:73], v[178:181], v[228:231], v[70:73]
	v_mfma_f32_16x16x32_bf16 v[66:69], v[186:189], v[228:231], v[66:69]
	s_setprio 0
	s_barrier
; #define PG8_STAGE(bufoff, gbase, voff) do { _Pragma("unroll") for (int _i = 0; _i < 2; ++_i) \
;         __builtin_amdgcn_global_load_lds((const unsigned*)((const char*)(gbase) + (voff)[_i]), (LAS unsigned*)(lds + (bufoff) + ldsw + _i * 8192), 16, 0, 0); } while (0)
; #define PG8_LDA(dst, b, h) do { _Pragma("unroll") for (int m = 0; m < 4; ++m) _Pragma("unroll") for (int k = 0; k < 2; ++k) dst[m][k] = *(const LAS bf16x8*)(lds + PG8_SA(b, h) + aoff + m * 2048 + k * 1024); } while (0)
; #define PG8_MMA(ai, bj, At, Bt) do { __builtin_amdgcn_s_setprio(1); _Pragma("unroll") for (int m = 0; m < 4; ++m) _Pragma("unroll") for (int n = 0; n < 2; ++n) _Pragma("unroll") for (int k = 0; k < 2; ++k) \
;         acc[ai][bj][m][n] = __builtin_amdgcn_mfma_f32_16x16x32_bf16(Bt[n][k], At[m][k], acc[ai][bj][m][n], 0, 0, 0); __builtin_amdgcn_s_setprio(0); } while (0)
; #define PG8_WAIT_V(n) asm volatile("s_waitcnt vmcnt(" #n ")" ::: "memory")
; #define PG8_WAIT_L(n) asm volatile("s_waitcnt lgkmcnt(" #n ")" ::: "memory")
; #define PG8_BAR __builtin_amdgcn_s_barrier()
; #define PG8_SCHED __builtin_amdgcn_sched_barrier(0)
; template <class Epi, class Sched, bool ALIGN_EPI = false, bool SP2 = false>
; __device__ __forceinline__ void gemm_phase(LAS unsigned char* lds, const Gemm g, const Sched& S, const Epi& E, const int tid) {
;     ...
;         for (int t = 0; t < nt; t += 2) {
;             const bool last = (t == nt - 2);
;             const char* a1 = cA + (size_t)(t + 1) * kstep;
;             const char* a2 = last ? nA : cA + (size_t)(t + 2) * kstep; const char* b2 = last ? nB : cB + (size_t)(t + 2) * kstep;
;             const char* a3 = a2 + kstep; const char* b3 = b2 + kstep;
;     ...
;             PG8_LDA(At, 1, 1); PG8_STAGE(PG8_SB(1, 0), b3, voffB); PG8_STAGE(PG8_SB(1, 1), b3 + hstep, voffB); PG8_STAGE(PG8_SA(1, 0), a3, voffA);
;             PG8_WAIT_V(8); PG8_WAIT_L(0); PG8_BAR; PG8_MMA(1, 0, At, B0); PG8_MMA(1, 1, At, B1); PG8_BAR; PG8_SCHED;
	s_add_i32 s28, s49, s34
	v_lshl_add_u64 v[160:161], v[160:161], 0, s[0:1]
	s_mov_b32 m0, s28
	ds_read_b128 v[190:193], v155 offset:49152
	ds_read_b128 v[194:197], v155 offset:50176
	ds_read_b128 v[208:211], v155 offset:51200
	ds_read_b128 v[212:215], v155 offset:52224
	ds_read_b128 v[216:219], v155 offset:53248
	ds_read_b128 v[220:223], v155 offset:54272
	ds_read_b128 v[224:227], v155 offset:55296
	ds_read_b128 v[228:231], v155 offset:56320
	global_load_lds_dwordx4 v[160:161], off
	s_add_i32 m0, s28, 0x2000
	s_add_u32 s26, s26, 0x40080
	v_lshl_add_u64 v[160:161], v[198:199], 0, s[0:1]
	s_addc_u32 s27, s27, 0
	s_add_i32 s28, s93, s34
	global_load_lds_dwordx4 v[160:161], off
	v_lshl_add_u64 v[160:161], s[26:27], 0, v[0:1]
	s_mov_b32 m0, s28
	s_nop 0
	global_load_lds_dwordx4 v[160:161], off
	v_lshl_add_u64 v[160:161], s[26:27], 0, v[130:131]
	s_add_i32 m0, s28, 0x2000
	s_nop 0
	global_load_lds_dwordx4 v[160:161], off
	v_lshl_add_u64 v[160:161], v[232:233], 0, s[0:1]
	s_mov_b32 m0, s39
	s_nop 0
	global_load_lds_dwordx4 v[160:161], off
	v_lshl_add_u64 v[160:161], v[234:235], 0, s[0:1]
	s_mov_b32 m0, s40
	s_nop 0
	global_load_lds_dwordx4 v[160:161], off
	s_waitcnt vmcnt(8)
	s_waitcnt lgkmcnt(0)
	s_barrier
	s_setprio 1
	s_waitcnt lgkmcnt(0)
	v_mfma_f32_16x16x32_bf16 v[62:65], v[140:143], v[190:193], v[62:65]
	v_mfma_f32_16x16x32_bf16 v[58:61], v[148:151], v[190:193], v[58:61]
	v_mfma_f32_16x16x32_bf16 v[46:49], v[140:143], v[208:211], v[46:49]
	v_mfma_f32_16x16x32_bf16 v[42:45], v[148:151], v[208:211], v[42:45]
	v_mfma_f32_16x16x32_bf16 v[30:33], v[140:143], v[216:219], v[30:33]
	v_mfma_f32_16x16x32_bf16 v[26:29], v[148:151], v[216:219], v[26:29]
	v_mfma_f32_16x16x32_bf16 v[14:17], v[140:143], v[224:227], v[14:17]
	v_mfma_f32_16x16x32_bf16 v[10:13], v[148:151], v[224:227], v[10:13]
	v_mfma_f32_16x16x32_bf16 v[62:65], v[144:147], v[194:197], v[62:65]
	v_mfma_f32_16x16x32_bf16 v[58:61], v[156:159], v[194:197], v[58:61]
	v_mfma_f32_16x16x32_bf16 v[46:49], v[144:147], v[212:215], v[46:49]
	v_mfma_f32_16x16x32_bf16 v[42:45], v[156:159], v[212:215], v[42:45]
	v_mfma_f32_16x16x32_bf16 v[30:33], v[144:147], v[220:223], v[30:33]
	v_mfma_f32_16x16x32_bf16 v[26:29], v[156:159], v[220:223], v[26:29]
	v_mfma_f32_16x16x32_bf16 v[14:17], v[144:147], v[228:231], v[14:17]
	v_mfma_f32_16x16x32_bf16 v[10:13], v[156:159], v[228:231], v[10:13]
	s_setprio 0
	s_setprio 1
	v_mfma_f32_16x16x32_bf16 v[54:57], v[174:177], v[190:193], v[54:57]
	v_mfma_f32_16x16x32_bf16 v[50:53], v[182:185], v[190:193], v[50:53]
	v_mfma_f32_16x16x32_bf16 v[38:41], v[174:177], v[208:211], v[38:41]
	v_mfma_f32_16x16x32_bf16 v[34:37], v[182:185], v[208:211], v[34:37]
	v_mfma_f32_16x16x32_bf16 v[22:25], v[174:177], v[216:219], v[22:25]
	v_mfma_f32_16x16x32_bf16 v[18:21], v[182:185], v[216:219], v[18:21]
	v_mfma_f32_16x16x32_bf16 v[6:9], v[174:177], v[224:227], v[6:9]
	v_mfma_f32_16x16x32_bf16 v[2:5], v[182:185], v[224:227], v[2:5]
	v_mfma_f32_16x16x32_bf16 v[54:57], v[178:181], v[194:197], v[54:57]
	v_mfma_f32_16x16x32_bf16 v[50:53], v[186:189], v[194:197], v[50:53]
	v_mfma_f32_16x16x32_bf16 v[38:41], v[178:181], v[212:215], v[38:41]
	v_mfma_f32_16x16x32_bf16 v[34:37], v[186:189], v[212:215], v[34:37]
	v_mfma_f32_16x16x32_bf16 v[22:25], v[178:181], v[220:223], v[22:25]
	v_mfma_f32_16x16x32_bf16 v[18:21], v[186:189], v[220:223], v[18:21]
	v_mfma_f32_16x16x32_bf16 v[6:9], v[178:181], v[228:231], v[6:9]
	v_mfma_f32_16x16x32_bf16 v[2:5], v[186:189], v[228:231], v[2:5]
	s_setprio 0
	s_add_i32 s48, s48, 2
	s_add_u32 s24, s24, 0x100
	s_addc_u32 s25, s25, 0
	s_add_u32 s46, s46, 0x100
	s_addc_u32 s47, s47, 0
	s_cmp_gt_u32 s48, 13
	s_barrier
	s_cbranch_scc0 .LBB0_1282
	s_and_b64 vcc, exec, s[12:13]
	s_cbranch_vccz .LBB0_1285
	s_barrier

; #define PG8_STAGE(bufoff, gbase, voff) do { _Pragma("unroll") for (int _i = 0; _i < 2; ++_i) \
;         __builtin_amdgcn_global_load_lds((const unsigned*)((const char*)(gbase) + (voff)[_i]), (LAS unsigned*)(lds + (bufoff) + ldsw + _i * 8192), 16, 0, 0); } while (0)
; #define PG8_LDA(dst, b, h) do { _Pragma("unroll") for (int m = 0; m < 4; ++m) _Pragma("unroll") for (int k = 0; k < 2; ++k) dst[m][k] = *(const LAS bf16x8*)(lds + PG8_SA(b, h) + aoff + m * 2048 + k * 1024); } while (0)
; #define PG8_LDB(dst, b, h) do { _Pragma("unroll") for (int n = 0; n < 2; ++n) _Pragma("unroll") for (int k = 0; k < 2; ++k) dst[n][k] = *(const LAS bf16x8*)(lds + PG8_SB(b, h) + boff + n * 2048 + k * 1024); } while (0)
; #define PG8_MMA(ai, bj, At, Bt) do { __builtin_amdgcn_s_setprio(1); _Pragma("unroll") for (int m = 0; m < 4; ++m) _Pragma("unroll") for (int n = 0; n < 2; ++n) _Pragma("unroll") for (int k = 0; k < 2; ++k) \
;         acc[ai][bj][m][n] = __builtin_amdgcn_mfma_f32_16x16x32_bf16(Bt[n][k], At[m][k], acc[ai][bj][m][n], 0, 0, 0); __builtin_amdgcn_s_setprio(0); } while (0)
; #define PG8_WAIT_V(n) asm volatile("s_waitcnt vmcnt(" #n ")" ::: "memory")
; #define PG8_WAIT_L(n) asm volatile("s_waitcnt lgkmcnt(" #n ")" ::: "memory")
; #define PG8_BAR __builtin_amdgcn_s_barrier()
; #define PG8_SCHED __builtin_amdgcn_sched_barrier(0)
; template <class Epi, class Sched, bool ALIGN_EPI = false, bool SP2 = false>
; __device__ __forceinline__ void gemm_phase(LAS unsigned char* lds, const Gemm g, const Sched& S, const Epi& E, const int tid) {
;     ...
;             PG8_LDB(B0, 0, 0); PG8_LDB(B1, 0, 1); PG8_SCHED; PG8_LDA(At, 0, 0); PG8_STAGE(PG8_SA(1, 1), a1 + hstep, voffA);
;             PG8_WAIT_V(8); PG8_WAIT_L(0); PG8_BAR; PG8_MMA(0, 0, At, B0); PG8_MMA(0, 1, At, B1); PG8_BAR; PG8_SCHED;
;             PG8_LDA(At, 0, 1); PG8_STAGE(PG8_SB(0, 0), b2, voffB); PG8_STAGE(PG8_SB(0, 1), b2 + hstep, voffB); PG8_STAGE(PG8_SA(0, 0), a2, voffA);
.LBB0_1367:
	s_add_u32 s10, s8, 0xfff00080
	s_addc_u32 s11, s9, -1
	s_add_i32 s60, 0, 0x10000
	s_cmp_eq_u32 s59, 60
	s_cselect_b32 s31, s25, s11
	s_cselect_b32 s30, s46, s10
	s_cselect_b32 s11, s23, s49
	s_cselect_b32 s10, s47, s48
	s_add_i32 s62, 0, 0x14000
	v_add_u32_e32 v154, s60, v181
	v_add_u32_e32 v178, s62, v181
	ds_read_b128 v[130:133], v154
	ds_read_b128 v[134:137], v154 offset:1024
	ds_read_b128 v[138:141], v154 offset:2048
	ds_read_b128 v[154:157], v154 offset:3072
	ds_read_b128 v[158:161], v178
	ds_read_b128 v[174:177], v178 offset:1024
	ds_read_b128 v[184:187], v178 offset:2048
	ds_read_b128 v[188:191], v178 offset:3072
	v_lshl_add_u64 v[178:179], s[8:9], 0, v[150:151]
	s_add_i32 m0, s37, 0xc000
	ds_read_b128 v[192:195], v183
	ds_read_b128 v[196:199], v183 offset:1024
	ds_read_b128 v[208:211], v183 offset:2048
	ds_read_b128 v[212:215], v183 offset:3072
	ds_read_b128 v[216:219], v183 offset:4096
	ds_read_b128 v[220:223], v183 offset:5120
	ds_read_b128 v[224:227], v183 offset:6144
	ds_read_b128 v[228:231], v183 offset:7168
	global_load_lds_dwordx4 v[178:179], off
	v_lshl_add_u64 v[178:179], s[8:9], 0, v[152:153]
	s_add_i32 m0, s37, 0xe000
	s_nop 0
	global_load_lds_dwordx4 v[178:179], off
	s_waitcnt vmcnt(8)
	s_waitcnt lgkmcnt(0)
	s_barrier
	s_setprio 1
	s_waitcnt lgkmcnt(0)
	v_mfma_f32_16x16x32_bf16 v[126:129], v[130:133], v[192:195], v[126:129]
	v_mfma_f32_16x16x32_bf16 v[122:125], v[138:141], v[192:195], v[122:125]
	v_mfma_f32_16x16x32_bf16 v[110:113], v[130:133], v[208:211], v[110:113]
	v_mfma_f32_16x16x32_bf16 v[106:109], v[138:141], v[208:211], v[106:109]
	v_mfma_f32_16x16x32_bf16 v[94:97], v[130:133], v[216:219], v[94:97]
	v_mfma_f32_16x16x32_bf16 v[90:93], v[138:141], v[216:219], v[90:93]
	v_mfma_f32_16x16x32_bf16 v[78:81], v[130:133], v[224:227], v[78:81]
	v_mfma_f32_16x16x32_bf16 v[74:77], v[138:141], v[224:227], v[74:77]
	v_mfma_f32_16x16x32_bf16 v[126:129], v[134:137], v[196:199], v[126:129]
	v_mfma_f32_16x16x32_bf16 v[122:125], v[154:157], v[196:199], v[122:125]
	v_mfma_f32_16x16x32_bf16 v[110:113], v[134:137], v[212:215], v[110:113]
	v_mfma_f32_16x16x32_bf16 v[106:109], v[154:157], v[212:215], v[106:109]
	v_mfma_f32_16x16x32_bf16 v[94:97], v[134:137], v[220:223], v[94:97]
	v_mfma_f32_16x16x32_bf16 v[90:93], v[154:157], v[220:223], v[90:93]
	v_mfma_f32_16x16x32_bf16 v[78:81], v[134:137], v[228:231], v[78:81]
	v_mfma_f32_16x16x32_bf16 v[74:77], v[154:157], v[228:231], v[74:77]
	s_setprio 0
	s_setprio 1
	v_mfma_f32_16x16x32_bf16 v[118:121], v[158:161], v[192:195], v[118:121]
	v_mfma_f32_16x16x32_bf16 v[114:117], v[184:187], v[192:195], v[114:117]
	v_mfma_f32_16x16x32_bf16 v[102:105], v[158:161], v[208:211], v[102:105]
	v_mfma_f32_16x16x32_bf16 v[98:101], v[184:187], v[208:211], v[98:101]
	v_mfma_f32_16x16x32_bf16 v[86:89], v[158:161], v[216:219], v[86:89]
	v_mfma_f32_16x16x32_bf16 v[82:85], v[184:187], v[216:219], v[82:85]
	v_mfma_f32_16x16x32_bf16 v[70:73], v[158:161], v[224:227], v[70:73]
	v_mfma_f32_16x16x32_bf16 v[66:69], v[184:187], v[224:227], v[66:69]
	v_mfma_f32_16x16x32_bf16 v[118:121], v[174:177], v[196:199], v[118:121]
	v_mfma_f32_16x16x32_bf16 v[114:117], v[188:191], v[196:199], v[114:117]
	v_mfma_f32_16x16x32_bf16 v[102:105], v[174:177], v[212:215], v[102:105]
	v_mfma_f32_16x16x32_bf16 v[98:101], v[188:191], v[212:215], v[98:101]
	v_mfma_f32_16x16x32_bf16 v[86:89], v[174:177], v[220:223], v[86:89]
	v_mfma_f32_16x16x32_bf16 v[82:85], v[188:191], v[220:223], v[82:85]
	v_mfma_f32_16x16x32_bf16 v[70:73], v[174:177], v[228:231], v[70:73]
	v_mfma_f32_16x16x32_bf16 v[66:69], v[188:191], v[228:231], v[66:69]
	s_setprio 0
	s_barrier
	s_add_i32 s60, s60, s36
	v_lshl_add_u64 v[178:179], s[10:11], 0, v[0:1]
	s_mov_b32 m0, s60
	ds_read_b128 v[192:195], v183 offset:16384
	ds_read_b128 v[196:199], v183 offset:17408
	ds_read_b128 v[208:211], v183 offset:18432
	ds_read_b128 v[212:215], v183 offset:19456
	ds_read_b128 v[216:219], v183 offset:20480
	ds_read_b128 v[220:223], v183 offset:21504
	ds_read_b128 v[224:227], v183 offset:22528
	ds_read_b128 v[228:231], v183 offset:23552
	global_load_lds_dwordx4 v[178:179], off
	s_add_i32 m0, s60, 0x2000
	s_add_u32 s60, s10, 0x100000
	v_lshl_add_u64 v[232:233], s[10:11], 0, v[142:143]
	s_addc_u32 s61, s11, 0
	s_add_i32 s62, s62, s36
	global_load_lds_dwordx4 v[232:233], off
	v_lshl_add_u64 v[234:235], s[60:61], 0, v[0:1]
	s_mov_b32 m0, s62
	v_lshl_add_u64 v[236:237], s[30:31], 0, v[144:145]
	global_load_lds_dwordx4 v[234:235], off
	v_lshl_add_u64 v[234:235], s[60:61], 0, v[142:143]
	s_add_i32 m0, s62, 0x2000
	s_nop 0
	global_load_lds_dwordx4 v[234:235], off
	v_lshl_add_u64 v[234:235], s[30:31], 0, v[146:147]
	s_mov_b32 m0, s37
	s_nop 0
	global_load_lds_dwordx4 v[234:235], off
	s_mov_b32 m0, s38
	s_nop 0
	global_load_lds_dwordx4 v[236:237], off
	s_waitcnt vmcnt(8)
	s_waitcnt lgkmcnt(0)
	s_barrier
; #define PG8_STAGE(bufoff, gbase, voff) do { _Pragma("unroll") for (int _i = 0; _i < 2; ++_i) \
;         __builtin_amdgcn_global_load_lds((const unsigned*)((const char*)(gbase) + (voff)[_i]), (LAS unsigned*)(lds + (bufoff) + ldsw + _i * 8192), 16, 0, 0); } while (0)
; #define PG8_LDA(dst, b, h) do { _Pragma("unroll") for (int m = 0; m < 4; ++m) _Pragma("unroll") for (int k = 0; k < 2; ++k) dst[m][k] = *(const LAS bf16x8*)(lds + PG8_SA(b, h) + aoff + m * 2048 + k * 1024); } while (0)
; #define PG8_LDB(dst, b, h) do { _Pragma("unroll") for (int n = 0; n < 2; ++n) _Pragma("unroll") for (int k = 0; k < 2; ++k) dst[n][k] = *(const LAS bf16x8*)(lds + PG8_SB(b, h) + boff + n * 2048 + k * 1024); } while (0)
; #define PG8_MMA(ai, bj, At, Bt) do { __builtin_amdgcn_s_setprio(1); _Pragma("unroll") for (int m = 0; m < 4; ++m) _Pragma("unroll") for (int n = 0; n < 2; ++n) _Pragma("unroll") for (int k = 0; k < 2; ++k) \
;         acc[ai][bj][m][n] = __builtin_amdgcn_mfma_f32_16x16x32_bf16(Bt[n][k], At[m][k], acc[ai][bj][m][n], 0, 0, 0); __builtin_amdgcn_s_setprio(0); } while (0)
; #define PG8_WAIT_V(n) asm volatile("s_waitcnt vmcnt(" #n ")" ::: "memory")
; #define PG8_WAIT_L(n) asm volatile("s_waitcnt lgkmcnt(" #n ")" ::: "memory")
; #define PG8_BAR __builtin_amdgcn_s_barrier()
; #define PG8_SCHED __builtin_amdgcn_sched_barrier(0)
; template <class Epi, class Sched, bool ALIGN_EPI = false, bool SP2 = false>
; __device__ __forceinline__ void gemm_phase(LAS unsigned char* lds, const Gemm g, const Sched& S, const Epi& E, const int tid) {
;     ...
;             PG8_WAIT_V(8); PG8_WAIT_L(0); PG8_BAR; PG8_MMA(1, 0, At, B0); PG8_MMA(1, 1, At, B1); PG8_BAR; PG8_SCHED;
;             PG8_LDB(B0, 1, 0); PG8_LDB(B1, 1, 1); PG8_SCHED; PG8_LDA(At, 1, 0); PG8_STAGE(PG8_SA(0, 1), a2 + hstep, voffA);
;             PG8_WAIT_V(8); PG8_WAIT_L(0); PG8_BAR; PG8_MMA(0, 0, At, B0); PG8_MMA(0, 1, At, B1); PG8_BAR; PG8_SCHED;
	s_setprio 1
	s_waitcnt lgkmcnt(0)
	v_mfma_f32_16x16x32_bf16 v[62:65], v[130:133], v[192:195], v[62:65]
	v_mfma_f32_16x16x32_bf16 v[58:61], v[138:141], v[192:195], v[58:61]
	v_mfma_f32_16x16x32_bf16 v[46:49], v[130:133], v[208:211], v[46:49]
	v_mfma_f32_16x16x32_bf16 v[42:45], v[138:141], v[208:211], v[42:45]
	v_mfma_f32_16x16x32_bf16 v[30:33], v[130:133], v[216:219], v[30:33]
	v_mfma_f32_16x16x32_bf16 v[26:29], v[138:141], v[216:219], v[26:29]
	v_mfma_f32_16x16x32_bf16 v[14:17], v[130:133], v[224:227], v[14:17]
	v_mfma_f32_16x16x32_bf16 v[10:13], v[138:141], v[224:227], v[10:13]
	v_mfma_f32_16x16x32_bf16 v[62:65], v[134:137], v[196:199], v[62:65]
	v_mfma_f32_16x16x32_bf16 v[58:61], v[154:157], v[196:199], v[58:61]
	v_mfma_f32_16x16x32_bf16 v[46:49], v[134:137], v[212:215], v[46:49]
	v_mfma_f32_16x16x32_bf16 v[42:45], v[154:157], v[212:215], v[42:45]
	v_mfma_f32_16x16x32_bf16 v[30:33], v[134:137], v[220:223], v[30:33]
	v_mfma_f32_16x16x32_bf16 v[26:29], v[154:157], v[220:223], v[26:29]
	v_mfma_f32_16x16x32_bf16 v[14:17], v[134:137], v[228:231], v[14:17]
	v_mfma_f32_16x16x32_bf16 v[10:13], v[154:157], v[228:231], v[10:13]
	s_setprio 0
	s_setprio 1
	v_mfma_f32_16x16x32_bf16 v[54:57], v[158:161], v[192:195], v[54:57]
	v_mfma_f32_16x16x32_bf16 v[50:53], v[184:187], v[192:195], v[50:53]
	v_mfma_f32_16x16x32_bf16 v[38:41], v[158:161], v[208:211], v[38:41]
	v_mfma_f32_16x16x32_bf16 v[34:37], v[184:187], v[208:211], v[34:37]
	v_mfma_f32_16x16x32_bf16 v[22:25], v[158:161], v[216:219], v[22:25]
	v_mfma_f32_16x16x32_bf16 v[18:21], v[184:187], v[216:219], v[18:21]
	v_mfma_f32_16x16x32_bf16 v[6:9], v[158:161], v[224:227], v[6:9]
	v_mfma_f32_16x16x32_bf16 v[2:5], v[184:187], v[224:227], v[2:5]
	v_mfma_f32_16x16x32_bf16 v[54:57], v[174:177], v[196:199], v[54:57]
	v_mfma_f32_16x16x32_bf16 v[50:53], v[188:191], v[196:199], v[50:53]
	v_mfma_f32_16x16x32_bf16 v[38:41], v[174:177], v[212:215], v[38:41]
	v_mfma_f32_16x16x32_bf16 v[34:37], v[188:191], v[212:215], v[34:37]
	v_mfma_f32_16x16x32_bf16 v[22:25], v[174:177], v[220:223], v[22:25]
	v_mfma_f32_16x16x32_bf16 v[18:21], v[188:191], v[220:223], v[18:21]
	v_mfma_f32_16x16x32_bf16 v[6:9], v[174:177], v[228:231], v[6:9]
	v_mfma_f32_16x16x32_bf16 v[2:5], v[188:191], v[228:231], v[2:5]
	s_setprio 0
	s_barrier
	s_add_i32 s60, 0, 0x18000
	v_add_u32_e32 v154, s60, v181
	v_add_u32_e32 v188, s93, v181
	ds_read_b128 v[130:133], v154
	ds_read_b128 v[134:137], v154 offset:1024
	ds_read_b128 v[138:141], v154 offset:2048
	ds_read_b128 v[154:157], v154 offset:3072
	ds_read_b128 v[158:161], v188
	ds_read_b128 v[174:177], v188 offset:1024
	ds_read_b128 v[184:187], v188 offset:2048
	ds_read_b128 v[188:191], v188 offset:3072
	s_add_u32 s30, s30, 0x100000
	s_addc_u32 s31, s31, 0
	s_mov_b32 m0, s39
	v_lshl_add_u64 v[238:239], s[30:31], 0, v[146:147]
	ds_read_b128 v[192:195], v183 offset:32768
	ds_read_b128 v[196:199], v183 offset:33792
	ds_read_b128 v[208:211], v183 offset:34816
	ds_read_b128 v[212:215], v183 offset:35840
	ds_read_b128 v[216:219], v183 offset:36864
	ds_read_b128 v[220:223], v183 offset:37888
	ds_read_b128 v[224:227], v183 offset:38912
	ds_read_b128 v[228:231], v183 offset:39936
	global_load_lds_dwordx4 v[238:239], off
	v_lshl_add_u64 v[238:239], s[30:31], 0, v[144:145]
	s_mov_b32 m0, s40
	s_nop 0
	global_load_lds_dwordx4 v[238:239], off
	s_waitcnt vmcnt(8)
	s_waitcnt lgkmcnt(0)
	s_barrier
	s_setprio 1
	s_waitcnt lgkmcnt(0)
	v_mfma_f32_16x16x32_bf16 v[126:129], v[130:133], v[192:195], v[126:129]
	v_mfma_f32_16x16x32_bf16 v[122:125], v[138:141], v[192:195], v[122:125]
	v_mfma_f32_16x16x32_bf16 v[110:113], v[130:133], v[208:211], v[110:113]
	v_mfma_f32_16x16x32_bf16 v[106:109], v[138:141], v[208:211], v[106:109]
	v_mfma_f32_16x16x32_bf16 v[94:97], v[130:133], v[216:219], v[94:97]
	v_mfma_f32_16x16x32_bf16 v[90:93], v[138:141], v[216:219], v[90:93]
	v_mfma_f32_16x16x32_bf16 v[78:81], v[130:133], v[224:227], v[78:81]
	v_mfma_f32_16x16x32_bf16 v[74:77], v[138:141], v[224:227], v[74:77]
	v_mfma_f32_16x16x32_bf16 v[126:129], v[134:137], v[196:199], v[126:129]
	v_mfma_f32_16x16x32_bf16 v[122:125], v[154:157], v[196:199], v[122:125]
	v_mfma_f32_16x16x32_bf16 v[110:113], v[134:137], v[212:215], v[110:113]
	v_mfma_f32_16x16x32_bf16 v[106:109], v[154:157], v[212:215], v[106:109]
	v_mfma_f32_16x16x32_bf16 v[94:97], v[134:137], v[220:223], v[94:97]
	v_mfma_f32_16x16x32_bf16 v[90:93], v[154:157], v[220:223], v[90:93]
	v_mfma_f32_16x16x32_bf16 v[78:81], v[134:137], v[228:231], v[78:81]
	v_mfma_f32_16x16x32_bf16 v[74:77], v[154:157], v[228:231], v[74:77]
	s_setprio 0
	s_setprio 1
	v_mfma_f32_16x16x32_bf16 v[118:121], v[158:161], v[192:195], v[118:121]
	v_mfma_f32_16x16x32_bf16 v[114:117], v[184:187], v[192:195], v[114:117]
	v_mfma_f32_16x16x32_bf16 v[102:105], v[158:161], v[208:211], v[102:105]
	v_mfma_f32_16x16x32_bf16 v[98:101], v[184:187], v[208:211], v[98:101]
	v_mfma_f32_16x16x32_bf16 v[86:89], v[158:161], v[216:219], v[86:89]
	v_mfma_f32_16x16x32_bf16 v[82:85], v[184:187], v[216:219], v[82:85]
	v_mfma_f32_16x16x32_bf16 v[70:73], v[158:161], v[224:227], v[70:73]
	v_mfma_f32_16x16x32_bf16 v[66:69], v[184:187], v[224:227], v[66:69]
	v_mfma_f32_16x16x32_bf16 v[118:121], v[174:177], v[196:199], v[118:121]
	v_mfma_f32_16x16x32_bf16 v[114:117], v[188:191], v[196:199], v[114:117]
	v_mfma_f32_16x16x32_bf16 v[102:105], v[174:177], v[212:215], v[102:105]
	v_mfma_f32_16x16x32_bf16 v[98:101], v[188:191], v[212:215], v[98:101]
	v_mfma_f32_16x16x32_bf16 v[86:89], v[174:177], v[220:223], v[86:89]
	v_mfma_f32_16x16x32_bf16 v[82:85], v[188:191], v[220:223], v[82:85]
	v_mfma_f32_16x16x32_bf16 v[70:73], v[174:177], v[228:231], v[70:73]
	v_mfma_f32_16x16x32_bf16 v[66:69], v[188:191], v[228:231], v[66:69]
	s_setprio 0
	s_barrier
; #define PG8_STAGE(bufoff, gbase, voff) do { _Pragma("unroll") for (int _i = 0; _i < 2; ++_i) \
;         __builtin_amdgcn_global_load_lds((const unsigned*)((const char*)(gbase) + (voff)[_i]), (LAS unsigned*)(lds + (bufoff) + ldsw + _i * 8192), 16, 0, 0); } while (0)
; #define PG8_LDA(dst, b, h) do { _Pragma("unroll") for (int m = 0; m < 4; ++m) _Pragma("unroll") for (int k = 0; k < 2; ++k) dst[m][k] = *(const LAS bf16x8*)(lds + PG8_SA(b, h) + aoff + m * 2048 + k * 1024); } while (0)
; #define PG8_MMA(ai, bj, At, Bt) do { __builtin_amdgcn_s_setprio(1); _Pragma("unroll") for (int m = 0; m < 4; ++m) _Pragma("unroll") for (int n = 0; n < 2; ++n) _Pragma("unroll") for (int k = 0; k < 2; ++k) \
;         acc[ai][bj][m][n] = __builtin_amdgcn_mfma_f32_16x16x32_bf16(Bt[n][k], At[m][k], acc[ai][bj][m][n], 0, 0, 0); __builtin_amdgcn_s_setprio(0); } while (0)
; #define PG8_WAIT_V(n) asm volatile("s_waitcnt vmcnt(" #n ")" ::: "memory")
; #define PG8_WAIT_L(n) asm volatile("s_waitcnt lgkmcnt(" #n ")" ::: "memory")
; #define PG8_BAR __builtin_amdgcn_s_barrier()
; #define PG8_SCHED __builtin_amdgcn_sched_barrier(0)
; template <class Epi, class Sched, bool ALIGN_EPI = false, bool SP2 = false>
; __device__ __forceinline__ void gemm_phase(LAS unsigned char* lds, const Gemm g, const Sched& S, const Epi& E, const int tid) {
;     ...
;         for (int t = 0; t < nt; t += 2) {
;             const bool last = (t == nt - 2);
;             const char* a1 = cA + (size_t)(t + 1) * kstep;
;             const char* a2 = last ? nA : cA + (size_t)(t + 2) * kstep; const char* b2 = last ? nB : cB + (size_t)(t + 2) * kstep;
;             const char* a3 = a2 + kstep; const char* b3 = b2 + kstep;
;     ...
;             PG8_LDA(At, 1, 1); PG8_STAGE(PG8_SB(1, 0), b3, voffB); PG8_STAGE(PG8_SB(1, 1), b3 + hstep, voffB); PG8_STAGE(PG8_SA(1, 0), a3, voffA);
;             PG8_WAIT_V(8); PG8_WAIT_L(0); PG8_BAR; PG8_MMA(1, 0, At, B0); PG8_MMA(1, 1, At, B1); PG8_BAR; PG8_SCHED;
	s_add_i32 s30, s60, s36
	v_lshl_add_u64 v[178:179], v[178:179], 0, s[0:1]
	s_mov_b32 m0, s30
	ds_read_b128 v[192:195], v183 offset:49152
	ds_read_b128 v[196:199], v183 offset:50176
	ds_read_b128 v[208:211], v183 offset:51200
	ds_read_b128 v[212:215], v183 offset:52224
	ds_read_b128 v[216:219], v183 offset:53248
	ds_read_b128 v[220:223], v183 offset:54272
	ds_read_b128 v[224:227], v183 offset:55296
	ds_read_b128 v[228:231], v183 offset:56320
	global_load_lds_dwordx4 v[178:179], off
	s_add_i32 m0, s30, 0x2000
	s_add_u32 s10, s10, 0x100080
	v_lshl_add_u64 v[178:179], v[232:233], 0, s[0:1]
	s_addc_u32 s11, s11, 0
	s_add_i32 s30, s93, s36
	global_load_lds_dwordx4 v[178:179], off
	v_lshl_add_u64 v[178:179], s[10:11], 0, v[0:1]
	s_mov_b32 m0, s30
	s_nop 0
	global_load_lds_dwordx4 v[178:179], off
	v_lshl_add_u64 v[178:179], s[10:11], 0, v[142:143]
	s_add_i32 m0, s30, 0x2000
	s_nop 0
	global_load_lds_dwordx4 v[178:179], off
	v_lshl_add_u64 v[178:179], v[234:235], 0, s[0:1]
	s_mov_b32 m0, s41
	s_nop 0
	global_load_lds_dwordx4 v[178:179], off
	v_lshl_add_u64 v[178:179], v[236:237], 0, s[0:1]
	s_mov_b32 m0, s42
	s_nop 0
	global_load_lds_dwordx4 v[178:179], off
	s_waitcnt vmcnt(8)
	s_waitcnt lgkmcnt(0)
	s_barrier
	s_setprio 1
	s_waitcnt lgkmcnt(0)
	v_mfma_f32_16x16x32_bf16 v[62:65], v[130:133], v[192:195], v[62:65]
	v_mfma_f32_16x16x32_bf16 v[58:61], v[138:141], v[192:195], v[58:61]
	v_mfma_f32_16x16x32_bf16 v[46:49], v[130:133], v[208:211], v[46:49]
	v_mfma_f32_16x16x32_bf16 v[42:45], v[138:141], v[208:211], v[42:45]
	v_mfma_f32_16x16x32_bf16 v[30:33], v[130:133], v[216:219], v[30:33]
	v_mfma_f32_16x16x32_bf16 v[26:29], v[138:141], v[216:219], v[26:29]
	v_mfma_f32_16x16x32_bf16 v[14:17], v[130:133], v[224:227], v[14:17]
	v_mfma_f32_16x16x32_bf16 v[10:13], v[138:141], v[224:227], v[10:13]
	v_mfma_f32_16x16x32_bf16 v[62:65], v[134:137], v[196:199], v[62:65]
	v_mfma_f32_16x16x32_bf16 v[58:61], v[154:157], v[196:199], v[58:61]
	v_mfma_f32_16x16x32_bf16 v[46:49], v[134:137], v[212:215], v[46:49]
	v_mfma_f32_16x16x32_bf16 v[42:45], v[154:157], v[212:215], v[42:45]
	v_mfma_f32_16x16x32_bf16 v[30:33], v[134:137], v[220:223], v[30:33]
	v_mfma_f32_16x16x32_bf16 v[26:29], v[154:157], v[220:223], v[26:29]
	v_mfma_f32_16x16x32_bf16 v[14:17], v[134:137], v[228:231], v[14:17]
	v_mfma_f32_16x16x32_bf16 v[10:13], v[154:157], v[228:231], v[10:13]
	s_setprio 0
	s_setprio 1
	v_mfma_f32_16x16x32_bf16 v[54:57], v[158:161], v[192:195], v[54:57]
	v_mfma_f32_16x16x32_bf16 v[50:53], v[184:187], v[192:195], v[50:53]
	v_mfma_f32_16x16x32_bf16 v[38:41], v[158:161], v[208:211], v[38:41]
	v_mfma_f32_16x16x32_bf16 v[34:37], v[184:187], v[208:211], v[34:37]
	v_mfma_f32_16x16x32_bf16 v[22:25], v[158:161], v[216:219], v[22:25]
	v_mfma_f32_16x16x32_bf16 v[18:21], v[184:187], v[216:219], v[18:21]
	v_mfma_f32_16x16x32_bf16 v[6:9], v[158:161], v[224:227], v[6:9]
	v_mfma_f32_16x16x32_bf16 v[2:5], v[184:187], v[224:227], v[2:5]
	v_mfma_f32_16x16x32_bf16 v[54:57], v[174:177], v[196:199], v[54:57]
	v_mfma_f32_16x16x32_bf16 v[50:53], v[188:191], v[196:199], v[50:53]
	v_mfma_f32_16x16x32_bf16 v[38:41], v[174:177], v[212:215], v[38:41]
	v_mfma_f32_16x16x32_bf16 v[34:37], v[188:191], v[212:215], v[34:37]
	v_mfma_f32_16x16x32_bf16 v[22:25], v[174:177], v[220:223], v[22:25]
	v_mfma_f32_16x16x32_bf16 v[18:21], v[188:191], v[220:223], v[18:21]
	v_mfma_f32_16x16x32_bf16 v[6:9], v[174:177], v[228:231], v[6:9]
	v_mfma_f32_16x16x32_bf16 v[2:5], v[188:191], v[228:231], v[2:5]
	s_setprio 0
	s_add_i32 s59, s59, 2
	s_add_u32 s8, s8, 0x100
	s_addc_u32 s9, s9, 0
	s_add_u32 s48, s48, 0x100
	s_addc_u32 s49, s49, 0
	s_cmp_gt_u32 s59, 61
	s_barrier
	s_cbranch_scc0 .LBB0_1367
	s_and_b64 vcc, exec, s[18:19]
	s_cbranch_vccz .LBB0_1370
	s_barrier
